# grid barrier: last workgroup of an XCD signals every XCD flag directly (no top counter / generation hops); closing barrier dropped after fused last epilogue; final gain loads hoisted
# speedup vs baseline: 1.0207x; 1.0133x over previous
_Z14fwd_megakernel6Params:
	s_load_dwordx2 s[54:55], s[0:1], 0xd0
	s_load_dwordx4 s[4:7], s[0:1], 0xc0
	v_and_b32_e32 v214, 0x3ff, v0
	v_writelane_b32 v253, s2, 0
	v_writelane_b32 v255, 1, 20
	s_load_dword s33, s[0:1], 0xe8
	s_load_dwordx2 s[2:3], s[0:1], 0xe0
	v_cmp_gt_u32_e32 vcc, 16, v214
	s_waitcnt lgkmcnt(0)
	v_writelane_b32 v253, s4, 1
	s_nop 1
	v_writelane_b32 v253, s5, 2
	v_writelane_b32 v253, s6, 3
	v_writelane_b32 v253, s7, 4
	v_writelane_b32 v253, s2, 5
	s_nop 1
	v_writelane_b32 v253, s3, 6
	s_add_u32 s2, s0, 0xe0
	s_addc_u32 s3, s1, 0
	s_and_saveexec_b64 s[4:5], vcc
	v_lshl_add_u32 v1, v214, 2, 0
	v_add_u32_e32 v1, 0x23fc0, v1
	v_mov_b32_e32 v2, 0
	ds_write_b32 v1, v2
	s_or_b64 exec, exec, s[4:5]
	v_readlane_b32 s4, v253, 0
	s_cmp_eq_u32 s4, 0
	s_cselect_b64 s[4:5], -1, 0
	v_cmp_gt_u32_e32 vcc, 64, v214
	s_and_b64 s[6:7], s[4:5], vcc
	s_waitcnt lgkmcnt(0)
	s_barrier
	s_and_saveexec_b64 s[4:5], s[6:7]
	s_cbranch_execz .LBB0_6
	v_lshlrev_b32_e32 v2, 2, v214
	v_mov_b32_e32 v3, 0
	v_lshl_add_u64 v[4:5], s[54:55], 0, v[2:3]
	s_mov_b64 s[6:7], 0x80000
	v_subrev_u32_e32 v1, 64, v214
	v_lshl_add_u64 v[4:5], v[4:5], 0, s[6:7]
	s_mov_b64 s[6:7], 0
	s_mov_b64 s[8:9], 0x100
	s_movk_i32 s10, 0xd3f

.LBB0_612:
	s_or_b64 exec, exec, s[0:1]
	s_add_u32 s0, s54, 0xb600000
	s_addc_u32 s1, s55, 0
	v_writelane_b32 v253, s0, 50
	v_mbcnt_lo_u32_b32 v0, -1, 0
	v_mbcnt_hi_u32_b32 v218, -1, v0
	v_writelane_b32 v253, s1, 51
	s_add_u32 s0, s54, 0xfe00000
	v_writelane_b32 v253, s0, 52
	s_addc_u32 s0, s55, 0
	v_writelane_b32 v253, s0, 53
	s_add_u32 s0, s54, 0x12200000
	s_addc_u32 s1, s55, 0
	v_writelane_b32 v253, s0, 54
	v_and_b32_e32 v0, 64, v218
	s_mov_b32 s91, 0
	v_writelane_b32 v253, s1, 55
	s_add_u32 s0, s54, 0x18500000
	s_addc_u32 s1, s55, 0
	v_writelane_b32 v253, s0, 56
	v_mov_b32_e32 v177, 0
	v_mov_b32_e32 v215, 0x358637bd
	v_writelane_b32 v253, s1, 57
	s_add_u32 s0, s54, 0x1cd00000
	s_addc_u32 s1, s55, 0
	v_writelane_b32 v253, s0, 58
	v_mov_b32_e32 v216, 0x260
	v_mov_b32_e32 v217, 1
	v_writelane_b32 v253, s1, 59
	s_add_u32 s0, s54, 0x21e00000
	s_addc_u32 s1, s55, 0
	v_writelane_b32 v253, s0, 60
	v_add_u32_e32 v219, 64, v0
	v_mov_b32_e32 v226, 0xc000
	v_writelane_b32 v253, s1, 61
	s_add_u32 s0, s54, 0x24b00000
	s_addc_u32 s1, s55, 0
	v_writelane_b32 v253, s0, 62
	v_mov_b32_e32 v227, 0xf149f2ca
	v_mov_b32_e32 v252, 0x1200000
	v_writelane_b32 v253, s1, 63
	s_add_u32 s0, s54, 0x24300000
	s_addc_u32 s1, s55, 0
	v_writelane_b32 v254, s0, 0
	v_readlane_b32 s2, v253, 5
	s_add_u32 s4, s54, 0x3a000
	v_writelane_b32 v254, s1, 1
	v_readlane_b32 s3, v253, 6
	s_addc_u32 s5, s55, 0
	s_mul_i32 s0, s3, s2
	v_writelane_b32 v254, s4, 2
	s_mul_i32 s73, s0, s33
	s_ashr_i32 s0, s2, 31
	v_writelane_b32 v254, s5, 3
	v_writelane_b32 v254, s0, 4
	s_add_u32 s0, s54, 0x2200000
	s_addc_u32 s1, s55, 0
	v_writelane_b32 v254, s0, 5
	v_readlane_b32 s4, v253, 46
	v_readlane_b32 s5, v253, 47
	v_writelane_b32 v254, s1, 6
	s_add_u32 s0, s54, 0x3200000
	s_addc_u32 s1, s55, 0
	v_writelane_b32 v254, s0, 7
	v_mov_b32_e32 v230, 0xc00
	s_movk_i32 s72, 0x1000
	v_writelane_b32 v254, s1, 8
	s_add_u32 s0, s54, 0x8a00000
	s_addc_u32 s1, s55, 0
	v_writelane_b32 v254, s0, 9
	s_mov_b32 s92, 0xf800000
	s_movk_i32 s45, 0x2000
	v_writelane_b32 v254, s1, 10
	s_add_u32 s0, s54, 0x1e800000
	s_addc_u32 s1, s55, 0
	v_writelane_b32 v254, s0, 11
	s_movk_i32 s53, 0x2ff
	s_mov_b32 s93, 0xb000
	v_writelane_b32 v254, s1, 12
	s_add_u32 s0, s54, 0x20300000
	s_addc_u32 s1, s55, 0
	v_writelane_b32 v254, s0, 13
	s_cmpk_lg_i32 s2, 0x100
	s_mov_b32 s38, 0x42800000
	v_writelane_b32 v254, s1, 14
	s_cselect_b64 s[0:1], -1, 0
	v_writelane_b32 v254, s0, 15
	s_mov_b32 s39, 0x18680000
	s_mov_b32 s42, 0x42b504f3
	v_writelane_b32 v254, s1, 16
	s_and_b64 s[0:1], s[4:5], exec
	s_cselect_b32 s0, 0xc0, s2
	v_writelane_b32 v254, s0, 17
	s_add_u32 s0, s54, 0x100000
	v_writelane_b32 v254, s0, 18
	s_addc_u32 s0, s55, 0
	v_writelane_b32 v254, s0, 19
	s_add_u32 s0, s54, 0x1200000
	s_addc_u32 s1, s55, 0
	v_writelane_b32 v254, s0, 20
	s_movk_i32 s43, 0x5800
	s_mov_b64 s[74:75], -1
	v_writelane_b32 v254, s1, 21
	s_add_u32 s0, s56, 0x2000000
	s_addc_u32 s1, s57, 0
	v_writelane_b32 v254, s0, 22
	s_mov_b64 s[78:79], 0
	s_mov_b64 s[40:41], 0x80
	v_writelane_b32 v254, s1, 23
	s_xor_b64 s[0:1], s[4:5], -1
	v_writelane_b32 v254, s0, 24
	s_mov_b32 s44, 0x3e38aa3b
	s_mov_b32 s52, 0x3e0293ee
	v_writelane_b32 v254, s1, 25
	s_add_u32 s0, s54, 0x2a00000
	s_addc_u32 s1, s55, 0
	v_writelane_b32 v254, s0, 26
	s_mov_b32 s96, s91
	s_waitcnt lgkmcnt(0)
	v_writelane_b32 v254, s1, 27
	v_readlane_b32 s0, v253, 23
	v_readlane_b32 s6, v253, 29
	v_readlane_b32 s1, v253, 24
	v_readlane_b32 s7, v253, 30
	s_add_u32 s0, s6, 0x1000000
	s_addc_u32 s1, s7, 0
	v_writelane_b32 v254, s0, 28
	v_readlane_b32 s8, v253, 31
	v_readlane_b32 s9, v253, 32
	v_writelane_b32 v254, s1, 29
	s_add_u32 s0, s54, 0x5e00000
	s_addc_u32 s1, s55, 0
	v_writelane_b32 v254, s0, 30
	v_readlane_b32 s14, v253, 37
	v_readlane_b32 s15, v253, 38
	v_writelane_b32 v254, s1, 31
	s_add_u32 s0, s8, 0x5800000
	s_addc_u32 s1, s9, 0
	v_writelane_b32 v254, s0, 32
	s_barrier
	s_nop 0
	v_writelane_b32 v254, s1, 33
	s_add_u32 s0, s54, 0xa000000
	s_addc_u32 s1, s55, 0
	v_writelane_b32 v254, s0, 34
	v_readlane_b32 s2, v253, 25
	v_readlane_b32 s3, v253, 26
	v_writelane_b32 v254, s1, 35
	s_add_u32 s0, s14, 0x2c00000
	s_addc_u32 s1, s15, 0
	v_writelane_b32 v254, s0, 36
	s_ashr_i32 s89, s88, 31
	v_readlane_b32 s4, v253, 27
	v_writelane_b32 v254, s1, 37
	s_lshl_b64 s[0:1], s[88:89], 13
	v_writelane_b32 v254, s0, 38
	v_readlane_b32 s5, v253, 28
	v_readlane_b32 s10, v253, 33
	v_writelane_b32 v254, s1, 39
	s_lshl_b64 s[0:1], s[88:89], 12
	v_writelane_b32 v254, s0, 40
	v_readlane_b32 s11, v253, 34
	v_readlane_b32 s12, v253, 35
	v_writelane_b32 v254, s1, 41
	s_add_u32 s0, s54, 0x18741e00
	v_writelane_b32 v254, s0, 42
	s_addc_u32 s0, s55, 0
	v_writelane_b32 v254, s0, 43
	s_add_i32 s0, 0, 0x23fc0
	v_writelane_b32 v254, s0, 44
	s_add_i32 s0, 0, 0x23fc4
	v_writelane_b32 v254, s0, 45
	s_add_i32 s0, 0, 0x800
	v_writelane_b32 v254, s0, 46
	s_add_i32 s0, 0, 0x20000
	v_writelane_b32 v254, s0, 47
	v_writelane_b32 v254, s54, 48
	s_mov_b64 s[0:1], 0x100000
	v_readlane_b32 s13, v253, 36
	v_writelane_b32 v254, s55, 49
	v_writelane_b32 v254, s88, 50
	s_nop 1
	v_writelane_b32 v254, s89, 51
	v_writelane_b32 v254, s73, 52
	s_branch .LBB0_615
.LBB0_614:
	s_or_b64 exec, exec, s[2:3]
	v_readlane_b32 s2, v254, 55
	v_readlane_b32 s3, v254, 56
	s_mov_b32 s96, 1
	s_mov_b64 s[74:75], 0
	s_mov_b64 s[78:79], -1
	s_and_b64 vcc, exec, s[2:3]
	s_waitcnt lgkmcnt(0)
	s_barrier
	s_cbranch_vccz .LBB0_615
	s_getpc_b64 s[98:99]

.Lnrm_p1_exit:
.LBB0_620:
	s_waitcnt vmcnt(0)
	s_barrier
	s_mov_b64 s[2:3], exec
	v_readlane_b32 s4, v253, 42
	v_readlane_b32 s5, v253, 43
	s_and_b64 s[4:5], s[2:3], s[4:5]
	s_mov_b64 exec, s[4:5]
	s_cbranch_execz .LBB0_664
	v_readlane_b32 s6, v253, 39
	v_readlane_b32 s7, v253, 40
	v_readlane_b32 s8, v253, 41
	v_readlane_b32 s9, v255, 20
	v_mov_b32_e32 v0, 0x23fc0
	ds_read2_b32 v[4:5], v0 offset1:1
	s_add_i32 s9, s9, 1
	v_writelane_b32 v255, s9, 20
	s_lshl_b32 s10, s8, 8
	s_add_i32 s10, s10, 0x1400
	v_mov_b32_e32 v0, s10
	v_mov_b32_e32 v1, 1
	global_atomic_add v2, v0, v1, s[6:7] sc0
	buffer_inv sc1
	s_waitcnt vmcnt(0) lgkmcnt(0)
	v_readfirstlane_b32 s11, v2
	v_readfirstlane_b32 s15, v4
	v_readfirstlane_b32 s14, v5
	s_add_i32 s11, s11, 1
	s_mul_i32 s15, s15, s9
	s_cmp_lg_u32 s11, s15
	s_cbranch_scc1 .Lgb2_wait
	buffer_wbl2 sc1
	s_waitcnt vmcnt(0)
	s_mov_b64 exec, 0xffff
	v_mbcnt_lo_u32_b32 v3, -1, 0
	v_lshlrev_b32_e32 v3, 8, v3
	v_add_u32_e32 v3, 0x2480, v3
	v_mov_b32_e32 v1, 1
	global_atomic_add v3, v1, s[6:7]
	s_mov_b64 exec, 1
.Lgb2_wait:
	s_add_i32 s12, s9, -1
	s_mul_i32 s14, s14, s12
	s_lshl_b32 s10, s8, 8
	s_add_i32 s10, s10, 0x2480
	v_mov_b32_e32 v0, s10
	s_mov_b32 s11, 0
.Lgb2_spin:
	global_load_dword v2, v0, s[6:7] sc1
	s_waitcnt vmcnt(0)
	v_readfirstlane_b32 s15, v2
	s_cmp_ge_u32 s15, s14
	s_cbranch_scc1 .Lgb2_done
	s_sleep 1
	s_add_i32 s11, s11, 1
	s_cmp_lt_u32 s11, 0x400000
	s_cbranch_scc1 .Lgb2_spin
.Lgb2_done:
.LBB0_664:
	s_or_b64 exec, exec, s[2:3]
	v_mov_b32_e32 v138, v214
	s_xor_b64 s[2:3], s[74:75], -1
	s_waitcnt lgkmcnt(0)
	s_barrier
	v_writelane_b32 v254, s2, 55
	v_readfirstlane_b32 s5, v138
	v_readlane_b32 s24, v253, 0
	s_ashr_i32 s25, s5, 6
	v_writelane_b32 v254, s3, 56
	s_cmpk_gt_i32 s24, 0x23f
	s_mov_b32 s97, s91
	s_cbranch_scc1 .LBB0_680
	v_lshlrev_b32_e32 v0, 4, v138
	v_add_u32_e32 v1, 0x2000, v0
	v_ashrrev_i32_e32 v2, 31, v1
	v_lshrrev_b32_e32 v2, 22, v2
	v_add_u32_e32 v2, v1, v2
	v_ashrrev_i32_e32 v8, 10, v2
	v_mul_i32_i24_e32 v2, 0x400, v8
	v_sub_u32_e32 v1, v1, v2
	v_lshrrev_b32_e32 v2, 4, v1
	v_bitop3_b32 v1, v2, v1, 32 bitop3:0x6c
	v_ashrrev_i32_e32 v2, 31, v1
	v_lshrrev_b32_e32 v2, 26, v2
	v_add_u32_e32 v2, v1, v2
	v_lshlrev_b32_e32 v3, 3, v8
	v_ashrrev_i32_e32 v9, 6, v2
	v_and_b32_e32 v3, -16, v3
	s_lshl_b64 s[2:3], s[96:97], 24
	v_readlane_b32 s6, v253, 44
	v_add_u32_e32 v3, v9, v3
	s_add_u32 s26, s6, s2
	v_and_b32_e32 v4, 3, v9
	s_mov_b32 s2, 0xfffe0
	v_lshrrev_b32_e32 v5, 2, v3
	v_lshlrev_b32_e32 v6, 1, v3
	v_and_b32_e32 v2, 0xc0, v2
	v_and_or_b32 v4, v3, s2, v4
	v_and_b32_e32 v5, 4, v5
	v_and_b32_e32 v6, 24, v6
	v_sub_u32_e32 v1, v1, v2
	v_or3_b32 v4, v4, v5, v6
	v_lshlrev_b32_e32 v5, 5, v8
	v_ashrrev_i16_sdwa v1, v217, sext(v1) dst_sel:DWORD dst_unused:UNUSED_PAD src0_sel:DWORD src1_sel:BYTE_0
	v_and_b32_e32 v5, 32, v5
	v_bfe_i32 v10, v1, 0, 16
	v_add_lshl_u32 v1, v5, v10, 1
	v_lshl_add_u32 v128, v4, 12, v1
	v_lshl_add_u32 v130, v3, 12, v1
	v_bfe_i32 v1, v138, 27, 1
	v_lshrrev_b32_e32 v1, 22, v1
	v_add_u32_e32 v1, v0, v1
	v_and_b32_e32 v1, 0xfffffc00, v1
	v_sub_u32_e32 v0, v0, v1
	v_lshrrev_b32_e32 v1, 4, v0
	v_ashrrev_i32_e32 v2, 31, v138
	v_bitop3_b32 v0, v1, v0, 32 bitop3:0x6c
	v_lshrrev_b32_e32 v2, 26, v2
	v_ashrrev_i32_e32 v1, 31, v0
	v_add_u32_e32 v2, v138, v2
	v_lshrrev_b32_e32 v1, 26, v1
	v_ashrrev_i32_e32 v12, 6, v2
	v_add_u32_e32 v1, v0, v1
	v_lshlrev_b32_e32 v2, 3, v12
	v_readlane_b32 s7, v253, 45
	v_ashrrev_i32_e32 v11, 6, v1
	v_and_b32_e32 v2, -16, v2
	s_addc_u32 s27, s7, s3
	v_add_u32_e32 v2, v11, v2
	v_and_b32_e32 v3, 3, v11
	s_ashr_i32 s29, s24, 31
	v_and_or_b32 v3, v2, s2, v3
	s_lshr_b32 s2, s29, 29
	s_add_i32 s2, s24, s2
	s_ashr_i32 s3, s2, 3
	s_and_b32 s2, s2, -8
	s_ashr_i32 s6, s5, 8
	s_lshl_b32 s28, s25, 10
	s_sub_i32 s2, s24, s2
	s_cmp_lt_i32 s2, 0
	s_movk_i32 s4, 0x49
	s_cselect_b32 s4, s4, 0x48
	s_mul_i32 s2, s2, s4
	s_add_i32 s2, s2, s3
	s_ashr_i32 s3, s2, 31
	s_lshr_b32 s3, s3, 25
	v_lshrrev_b32_e32 v4, 2, v2
	v_lshlrev_b32_e32 v5, 1, v2
	v_and_b32_e32 v1, 0xc0, v1
	s_add_i32 s3, s2, s3
	v_and_b32_e32 v4, 4, v4
	v_and_b32_e32 v5, 24, v5
	v_sub_u32_e32 v0, v0, v1
	s_ashr_i32 s4, s3, 7
	v_or3_b32 v3, v3, v4, v5
	v_lshlrev_b32_e32 v4, 5, v12
	v_ashrrev_i16_sdwa v0, v217, sext(v0) dst_sel:DWORD dst_unused:UNUSED_PAD src0_sel:DWORD src1_sel:BYTE_0
	s_lshl_b32 s7, s4, 3
	v_and_b32_e32 v4, 32, v4
	v_bfe_i32 v13, v0, 0, 16
	s_sub_i32 s4, 36, s7
	v_add_lshl_u32 v0, v4, v13, 1
	s_min_u32 s8, s4, 8
	s_and_b32 s3, s3, 0xffffff80
	v_lshl_add_u32 v176, v3, 12, v0
	s_sub_i32 s9, s2, s3
	v_cvt_f32_ubyte0_e32 v3, s8
	v_cvt_f32_i32_e32 v1, s9
	v_rcp_iflag_f32_e32 v4, v3
	v_lshl_add_u32 v132, v2, 12, v0
	s_ashr_i32 s2, s9, 30
	s_or_b32 s4, s2, 1
	v_mul_f32_e32 v0, v1, v4
	v_trunc_f32_e32 v0, v0
	v_fma_f32 v1, -v0, v3, v1
	v_cvt_i32_f32_e32 v0, v0
	v_cmp_ge_f32_e64 s[2:3], |v1|, v3
	s_and_b64 s[2:3], s[2:3], exec
	s_cselect_b32 s2, s4, 0
	v_readfirstlane_b32 s3, v0
	s_add_i32 s4, s3, s2
	s_mul_i32 s2, s4, s8
	s_sub_i32 s2, s9, s2
	s_sext_i32_i8 s2, s2
	s_add_i32 s12, s7, s2
	s_ashr_i32 s13, s12, 31
	s_bfe_i64 s[8:9], s[4:5], 0x80000
	s_lshl_b64 s[2:3], s[12:13], 20
	s_lshl_b64 s[8:9], s[8:9], 20
	s_add_u32 s20, s26, s8
	s_addc_u32 s21, s27, s9
	s_add_i32 s13, s28, 0
	s_add_i32 m0, s13, 0x10000
	v_readlane_b32 s7, v253, 52
	global_load_lds_dwordx4 v176, s[20:21]
	s_add_i32 m0, s13, 0x12000
	s_add_u32 s8, s20, 0x80000
	global_load_lds_dwordx4 v128, s[20:21]
	s_addc_u32 s9, s21, 0
	s_add_i32 m0, s13, 0x14000
	v_mov_b32_e32 v129, v177
	global_load_lds_dwordx4 v176, s[8:9]
	s_add_i32 m0, s13, 0x16000
	s_add_u32 s18, s7, s2
	v_readlane_b32 s2, v253, 53
	s_addc_u32 s19, s2, s3
	s_add_i32 s30, s13, 0x2000
	global_load_lds_dwordx4 v128, s[8:9]
	s_mov_b32 m0, s13
	s_add_u32 s2, s18, 0x80000
	global_load_lds_dwordx4 v132, s[18:19]
	s_mov_b32 m0, s30
	s_addc_u32 s3, s19, 0
	s_add_i32 s31, s13, 0x4000
	global_load_lds_dwordx4 v130, s[18:19]
	s_mov_b32 m0, s31
	s_add_i32 s33, s13, 0x6000
	global_load_lds_dwordx4 v132, s[2:3]
	s_mov_b32 m0, s33
	v_mov_b32_e32 v133, v177
	global_load_lds_dwordx4 v130, s[2:3]
	v_mov_b32_e32 v131, v177
	s_cmp_eq_u32 s6, 1
	v_lshl_add_u64 v[6:7], s[20:21], 0, v[176:177]
	v_lshl_add_u64 v[4:5], s[20:21], 0, v[128:129]
	v_lshl_add_u64 v[0:1], s[18:19], 0, v[132:133]
	s_cselect_b64 s[2:3], -1, 0
	s_cmp_lg_u32 s6, 1
	v_lshl_add_u64 v[2:3], s[18:19], 0, v[130:131]
	s_cbranch_scc1 .LBB0_667
	s_barrier

.LBB0_945:
	s_waitcnt vmcnt(0)
	s_waitcnt vmcnt(0)
	s_barrier
	s_mov_b64 s[2:3], exec
	v_readlane_b32 s4, v253, 42
	v_readlane_b32 s5, v253, 43
	s_and_b64 s[4:5], s[2:3], s[4:5]
	s_mov_b64 exec, s[4:5]
	s_cbranch_execz .LBB0_989
	v_readlane_b32 s6, v253, 39
	v_readlane_b32 s7, v253, 40
	v_readlane_b32 s8, v253, 41
	v_readlane_b32 s9, v255, 20
	v_mov_b32_e32 v0, 0x23fc0
	ds_read2_b32 v[4:5], v0 offset1:1
	s_add_i32 s9, s9, 1
	v_writelane_b32 v255, s9, 20
	s_lshl_b32 s10, s8, 8
	s_add_i32 s10, s10, 0x1400
	v_mov_b32_e32 v0, s10
	v_mov_b32_e32 v1, 1
	global_atomic_add v2, v0, v1, s[6:7] sc0
	buffer_inv sc1
	s_waitcnt vmcnt(0) lgkmcnt(0)
	v_readfirstlane_b32 s11, v2
	v_readfirstlane_b32 s15, v4
	v_readfirstlane_b32 s14, v5
	s_add_i32 s11, s11, 1
	s_mul_i32 s15, s15, s9
	s_cmp_lg_u32 s11, s15
	s_cbranch_scc1 .Lgb3_wait
	s_mov_b64 exec, 0xffff
	v_mbcnt_lo_u32_b32 v3, -1, 0
	v_lshlrev_b32_e32 v3, 8, v3
	v_add_u32_e32 v3, 0x2480, v3
	v_mov_b32_e32 v1, 1
	global_atomic_add v3, v1, s[6:7]
	s_mov_b64 exec, 1

.Lgb3_done:
.LBB0_989:
	s_or_b64 exec, exec, s[2:3]
	v_mov_b32_e32 v0, v214
	v_readlane_b32 s3, v253, 0
	s_waitcnt lgkmcnt(0)
	s_barrier
	s_lshl_b32 s3, s3, 3
	v_readfirstlane_b32 s2, v0
	s_ashr_i32 s2, s2, 6
	s_add_i32 s2, s3, s2
	s_cmpk_gt_i32 s2, 0x23ff
	s_cbranch_scc1 .LBB0_1012
	v_and_b32_e32 v58, 63, v0
	v_lshlrev_b32_e32 v3, 3, v0
	v_bfe_u32 v1, v0, 2, 1
	v_and_b32_e32 v6, 24, v3
	v_mov_b32_e32 v3, s71
	v_mov_b32_e32 v5, s69
	v_cmp_gt_u32_e32 vcc, 48, v58
	v_lshlrev_b32_e32 v4, 6, v1
	v_lshlrev_b32_e32 v176, 8, v1
	v_cndmask_b32_e32 v9, v3, v5, vcc
	v_mov_b32_e32 v3, s70
	v_mov_b32_e32 v5, s68
	v_cmp_eq_u32_e64 s[6:7], 0, v1
	v_xor_b32_e32 v1, 1, v218
	v_cndmask_b32_e32 v8, v3, v5, vcc
	v_cmp_lt_i32_e32 vcc, v1, v219
	v_or_b32_e32 v3, 1, v6
	v_or_b32_e32 v5, 2, v6
	v_cndmask_b32_e32 v1, v218, v1, vcc
	v_lshlrev_b32_e32 v59, 2, v1
	v_xor_b32_e32 v1, 2, v218
	v_cmp_lt_i32_e32 vcc, v1, v219
	v_or_b32_e32 v7, 3, v6
	v_cvt_f32_ubyte0_e32 v3, v3
	v_cndmask_b32_e32 v1, v218, v1, vcc
	v_lshlrev_b32_e32 v60, 2, v1
	v_xor_b32_e32 v1, 4, v218
	v_cmp_lt_i32_e32 vcc, v1, v219
	v_cvt_f32_ubyte0_e32 v5, v5
	v_cvt_f32_ubyte0_e32 v7, v7
	v_cndmask_b32_e32 v1, v218, v1, vcc
	v_lshlrev_b32_e32 v61, 2, v1
	v_cvt_f32_ubyte0_e32 v1, v6
	v_mul_f32_e32 v1, 0xbed49a78, v1
	v_exp_f32_e32 v1, v1
	v_mul_f32_e32 v3, 0xbed49a78, v3
	v_mul_f32_e32 v5, 0xbed49a78, v5
	v_mul_f32_e32 v7, 0xbed49a78, v7
	v_exp_f32_e32 v3, v3
	v_exp_f32_e32 v5, v5
	v_exp_f32_e32 v7, v7
	v_mul_f32_e32 v62, 0.15915494, v1
	v_or_b32_e32 v1, 4, v6
	v_cvt_f32_ubyte0_e32 v1, v1
	v_mul_f32_e32 v1, 0xbed49a78, v1
	v_mul_f32_e32 v63, 0.15915494, v3
	v_mul_f32_e32 v64, 0.15915494, v5
	v_mul_f32_e32 v65, 0.15915494, v7
	v_exp_f32_e32 v1, v1
	v_or_b32_e32 v3, 5, v6
	v_or_b32_e32 v5, 6, v6
	v_or_b32_e32 v7, 7, v6
	v_cvt_f32_ubyte0_e32 v3, v3
	v_cvt_f32_ubyte0_e32 v5, v5
	v_cvt_f32_ubyte0_e32 v7, v7
	v_mul_f32_e32 v3, 0xbed49a78, v3
	v_mul_f32_e32 v5, 0xbed49a78, v5
	v_mul_f32_e32 v7, 0xbed49a78, v7
	s_lshl_b32 s90, s96, 7
	v_exp_f32_e32 v3, v3
	v_exp_f32_e32 v5, v5
	v_exp_f32_e32 v7, v7
	v_lshlrev_b32_e32 v2, 4, v0
	v_lshl_add_u64 v[8:9], s[90:91], 2, v[8:9]
	v_mul_f32_e32 v66, 0.15915494, v1
	v_lshlrev_b32_e32 v1, 5, v0
	v_and_b32_e32 v0, 1, v0
	v_lshl_add_u64 v[8:9], v[8:9], 0, v[176:177]
	v_lshlrev_b32_e32 v176, 2, v6
	v_lshlrev_b32_e32 v0, 4, v0
	s_movk_i32 s3, 0x7c0
	v_readlane_b32 s4, v253, 56
	v_and_b32_e32 v2, 0x380, v2
	v_lshl_add_u64 v[8:9], v[8:9], 0, v[176:177]
	v_and_or_b32 v176, v1, s3, v0
	v_readlane_b32 s5, v253, 57
	v_mul_f32_e32 v67, 0.15915494, v3
	v_mul_f32_e32 v68, 0.15915494, v5
	v_mul_f32_e32 v69, 0.15915494, v7
	v_lshlrev_b32_e32 v70, 3, v58
	v_lshl_add_u64 v[10:11], s[4:5], 0, v[176:177]
	v_lshlrev_b32_e32 v176, 1, v2
	v_lshlrev_b32_e32 v12, 1, v4
	v_lshlrev_b32_e32 v14, 1, v6
	s_branch .LBB0_992

.LBB0_1012:
	s_waitcnt vmcnt(0)
	s_barrier
	s_mov_b64 s[2:3], exec
	v_readlane_b32 s4, v253, 42
	v_readlane_b32 s5, v253, 43
	s_and_b64 s[4:5], s[2:3], s[4:5]
	s_mov_b64 exec, s[4:5]
	s_cbranch_execz .LBB0_1056
	v_readlane_b32 s6, v253, 39
	v_readlane_b32 s7, v253, 40
	v_readlane_b32 s8, v253, 41
	v_readlane_b32 s9, v255, 20
	v_mov_b32_e32 v0, 0x23fc0
	ds_read2_b32 v[4:5], v0 offset1:1
	s_add_i32 s9, s9, 1
	v_writelane_b32 v255, s9, 20
	s_lshl_b32 s10, s8, 8
	s_add_i32 s10, s10, 0x1400
	v_mov_b32_e32 v0, s10
	v_mov_b32_e32 v1, 1
	global_atomic_add v2, v0, v1, s[6:7] sc0
	buffer_inv sc1
	s_waitcnt vmcnt(0) lgkmcnt(0)
	v_readfirstlane_b32 s11, v2
	v_readfirstlane_b32 s15, v4
	v_readfirstlane_b32 s14, v5
	s_add_i32 s11, s11, 1
	s_mul_i32 s15, s15, s9
	s_cmp_lg_u32 s11, s15
	s_cbranch_scc1 .Lgb4_wait
	s_mov_b64 exec, 0xffff
	v_mbcnt_lo_u32_b32 v3, -1, 0
	v_lshlrev_b32_e32 v3, 8, v3
	v_add_u32_e32 v3, 0x2480, v3
	v_mov_b32_e32 v1, 1
	global_atomic_add v3, v1, s[6:7]
	s_mov_b64 exec, 1

.Lgb4_done:
.LBB0_1056:
	s_or_b64 exec, exec, s[2:3]
	s_and_b64 s[2:3], s[78:79], exec
	v_mov_b32_e32 v182, v214
	v_readlane_b32 s34, v253, 0
	s_movk_i32 s2, 0x240
	s_waitcnt lgkmcnt(0)
	s_barrier
	s_cselect_b32 s35, s2, 0x288
	s_cmpk_gt_i32 s34, 0xbf
	s_cselect_b64 s[2:3], -1, 0
	s_ashr_i32 s4, s34, 3
	s_mul_hi_i32 s5, s4, 0x2aaaaaab
	s_lshr_b32 s6, s5, 31
	s_add_i32 s5, s5, s6
	s_mul_i32 s6, s5, 6
	s_sub_i32 s4, s4, s6
	s_mul_i32 s5, s5, 48
	s_lshl_b32 s6, s4, 3
	s_sub_i32 s4, s34, s4
	s_mul_i32 s50, s34, 3
	s_add_i32 s5, s5, s6
	s_and_b32 s4, s4, 7
	s_addk_i32 s50, 0xff40
	s_add_i32 s49, s34, 0xc0
	s_or_b32 s36, s5, s4
	s_cmpk_gt_i32 s34, 0x47
	s_cselect_b64 s[56:57], -1, 0
	s_add_i32 s86, s34, 0x240
	s_mov_b32 s24, 0
	s_branch .LBB0_1060

.LBB0_1145:
	s_waitcnt vmcnt(0)
	s_barrier
	s_mov_b64 s[2:3], exec
	v_readlane_b32 s4, v253, 42
	v_readlane_b32 s5, v253, 43
	s_and_b64 s[4:5], s[2:3], s[4:5]
	s_mov_b64 exec, s[4:5]
	s_cbranch_execz .LBB0_1189
	v_readlane_b32 s6, v253, 39
	v_readlane_b32 s7, v253, 40
	v_readlane_b32 s8, v253, 41
	v_readlane_b32 s9, v255, 20
	v_mov_b32_e32 v0, 0x23fc0
	ds_read2_b32 v[4:5], v0 offset1:1
	s_add_i32 s9, s9, 1
	v_writelane_b32 v255, s9, 20
	s_lshl_b32 s10, s8, 8
	s_add_i32 s10, s10, 0x1400
	v_mov_b32_e32 v0, s10
	v_mov_b32_e32 v1, 1
	global_atomic_add v2, v0, v1, s[6:7] sc0
	buffer_inv sc1
	s_waitcnt vmcnt(0) lgkmcnt(0)
	v_readfirstlane_b32 s11, v2
	v_readfirstlane_b32 s15, v4
	v_readfirstlane_b32 s14, v5
	s_add_i32 s11, s11, 1
	s_mul_i32 s15, s15, s9
	s_cmp_lg_u32 s11, s15
	s_cbranch_scc1 .Lgb5_wait
	buffer_wbl2 sc1
	s_waitcnt vmcnt(0)
	s_mov_b64 exec, 0xffff
	v_mbcnt_lo_u32_b32 v3, -1, 0
	v_lshlrev_b32_e32 v3, 8, v3
	v_add_u32_e32 v3, 0x2480, v3
	v_mov_b32_e32 v1, 1
	global_atomic_add v3, v1, s[6:7]
	s_mov_b64 exec, 1

.Lgb5_done:
.LBB0_1189:
	s_or_b64 exec, exec, s[2:3]
	v_mov_b32_e32 v0, v214
	s_waitcnt lgkmcnt(0)
	s_barrier
	v_readlane_b32 s2, v253, 0
	v_and_b32_e32 v1, 63, v0
	v_lshl_or_b32 v176, s96, 6, v1
	v_lshlrev_b64 v[2:3], 2, v[176:177]
	v_lshl_add_u64 v[4:5], s[58:59], 0, v[2:3]
	global_load_dword v6, v[4:5], off
	v_lshl_add_u64 v[4:5], s[60:61], 0, v[2:3]
	global_load_dword v7, v[4:5], off
	v_lshl_add_u64 v[4:5], s[62:63], 0, v[2:3]
	v_lshl_add_u64 v[2:3], s[64:65], 0, v[2:3]
	global_load_dword v4, v[4:5], off
	v_xor_b32_e32 v5, 2, v218
	global_load_dword v2, v[2:3], off
	v_xor_b32_e32 v3, 1, v218
	v_cmp_lt_i32_e32 vcc, v3, v219
	v_xor_b32_e32 v9, 4, v218
	v_readfirstlane_b32 s3, v0
	v_cndmask_b32_e32 v3, v218, v3, vcc
	v_lshlrev_b32_e32 v231, 2, v3
	v_cmp_lt_i32_e32 vcc, v5, v219
	s_ashr_i32 s3, s3, 6
	s_lshl_b32 s2, s2, 3
	v_cndmask_b32_e32 v5, v218, v5, vcc
	v_lshlrev_b32_e32 v232, 2, v5
	v_cmp_lt_i32_e32 vcc, v9, v219
	v_xor_b32_e32 v5, 8, v218
	s_add_i32 s2, s2, s3
	v_cndmask_b32_e32 v9, v218, v9, vcc
	v_lshlrev_b32_e32 v233, 2, v9
	v_cmp_lt_i32_e32 vcc, v5, v219
	s_cmpk_gt_i32 s2, 0x23ff
	s_waitcnt vmcnt(0)
	v_mul_f32_e32 v3, v6, v7
	ds_bpermute_b32 v3, v231, v3
	v_cndmask_b32_e32 v5, v218, v5, vcc
	v_lshlrev_b32_e32 v234, 2, v5
	v_mul_f32_e32 v8, v4, v2
	ds_bpermute_b32 v8, v231, v8
	s_waitcnt lgkmcnt(1)
	v_fmac_f32_e32 v3, v6, v7
	v_xor_b32_e32 v7, 16, v218
	v_cmp_lt_i32_e32 vcc, v7, v219
	s_waitcnt lgkmcnt(0)
	v_fmac_f32_e32 v8, v4, v2
	ds_bpermute_b32 v2, v232, v3
	ds_bpermute_b32 v4, v232, v8
	v_cndmask_b32_e32 v7, v218, v7, vcc
	v_lshlrev_b32_e32 v235, 2, v7
	s_waitcnt lgkmcnt(1)
	v_add_f32_e32 v2, v3, v2
	s_waitcnt lgkmcnt(0)
	v_add_f32_e32 v3, v8, v4
	ds_bpermute_b32 v4, v233, v2
	ds_bpermute_b32 v6, v233, v3
	s_waitcnt lgkmcnt(1)
	v_add_f32_e32 v2, v2, v4
	s_waitcnt lgkmcnt(0)
	v_add_f32_e32 v3, v3, v6
	ds_bpermute_b32 v4, v234, v2
	ds_bpermute_b32 v5, v234, v3
	v_xor_b32_e32 v6, 32, v218
	v_cmp_lt_i32_e32 vcc, v6, v219
	s_waitcnt lgkmcnt(1)
	v_add_f32_e32 v2, v2, v4
	s_waitcnt lgkmcnt(0)
	v_add_f32_e32 v4, v3, v5
	ds_bpermute_b32 v3, v235, v2
	ds_bpermute_b32 v5, v235, v4
	v_cndmask_b32_e32 v6, v218, v6, vcc
	v_lshlrev_b32_e32 v236, 2, v6
	s_waitcnt lgkmcnt(1)
	v_add_f32_e32 v3, v2, v3
	s_waitcnt lgkmcnt(0)
	v_add_f32_e32 v0, v4, v5
	ds_bpermute_b32 v4, v236, v3
	ds_bpermute_b32 v2, v236, v0
	s_cbranch_scc1 .LBB0_1194
	s_waitcnt lgkmcnt(1)
	v_add_f32_e32 v3, v3, v4
	v_mul_f32_e32 v4, 0x3fb8aa3b, v3
	s_mov_b32 s3, 0x3fb8aa3b
	v_fma_f32 v5, v3, s3, -v4
	v_rndne_f32_e32 v6, v4
	v_fmac_f32_e32 v5, 0x32a5705f, v3
	v_sub_f32_e32 v4, v4, v6
	v_add_f32_e32 v4, v4, v5
	v_exp_f32_e32 v4, v4
	v_cvt_i32_f32_e32 v5, v6
	s_waitcnt lgkmcnt(0)
	v_add_f32_e32 v0, v0, v2
	v_mov_b32_e32 v6, 0x3eb60549
	v_mov_b32_e32 v7, 0x3e4ccccd
	v_mul_f32_e32 v2, 0x3fb8aa3b, v0
	v_cndmask_b32_e64 v6, v6, v7, s[74:75]
	v_ldexp_f32 v4, v4, v5
	v_fma_f32 v5, v0, s3, -v2
	v_rndne_f32_e32 v7, v2
	v_fmac_f32_e32 v5, 0x32a5705f, v0
	v_sub_f32_e32 v2, v2, v7
	v_add_f32_e32 v2, v2, v5
	v_exp_f32_e32 v2, v2
	v_cvt_i32_f32_e32 v5, v7
	s_mov_b32 s3, 0xc2ce8ed0
	v_cmp_ngt_f32_e32 vcc, s3, v3
	s_mov_b32 s4, 0x42b17218
	v_mov_b32_e32 v7, 0x7f800000
	v_cndmask_b32_e32 v4, 0, v4, vcc
	v_cmp_nlt_f32_e32 vcc, s4, v3
	v_ldexp_f32 v2, v2, v5
	v_lshlrev_b32_e32 v176, 2, v1
	v_cndmask_b32_e32 v3, v7, v4, vcc
	v_cmp_ngt_f32_e32 vcc, s3, v0
	s_nop 1
	v_cndmask_b32_e32 v2, 0, v2, vcc
	v_cmp_nlt_f32_e32 vcc, s4, v0
	v_readlane_b32 s4, v253, 60
	v_readlane_b32 s5, v253, 61
	v_cndmask_b32_e32 v0, v7, v2, vcc
	v_sub_f32_e32 v0, v3, v0
	v_lshl_add_u64 v[2:3], s[4:5], 0, v[176:177]
	v_readlane_b32 s4, v253, 58
	v_lshlrev_b32_e32 v176, 3, v1
	v_readlane_b32 s5, v253, 59
	v_add_f32_e32 v0, v6, v0
	v_mov_b32_e32 v1, v0
	v_lshl_add_u64 v[4:5], s[4:5], 0, v[176:177]
	v_readlane_b32 s4, v254, 11
	v_readlane_b32 s5, v254, 12
	s_nop 1
	v_lshl_add_u64 v[6:7], s[4:5], 0, v[176:177]
	v_readlane_b32 s4, v254, 13
	v_readlane_b32 s5, v254, 14
	s_nop 1
	v_lshl_add_u64 v[8:9], s[4:5], 0, v[176:177]
	s_branch .LBB0_1192

.LBB0_1194:
	s_waitcnt vmcnt(0)
	s_waitcnt lgkmcnt(0)
	s_barrier
	s_mov_b64 s[2:3], exec
	v_readlane_b32 s4, v253, 42
	v_readlane_b32 s5, v253, 43
	s_and_b64 s[4:5], s[2:3], s[4:5]
	s_mov_b64 exec, s[4:5]
	s_cbranch_execz .LBB0_1238
	v_readlane_b32 s6, v253, 39
	v_readlane_b32 s7, v253, 40
	v_readlane_b32 s8, v253, 41
	v_readlane_b32 s9, v255, 20
	v_mov_b32_e32 v0, 0x23fc0
	ds_read2_b32 v[4:5], v0 offset1:1
	s_add_i32 s9, s9, 1
	v_writelane_b32 v255, s9, 20
	s_lshl_b32 s10, s8, 8
	s_add_i32 s10, s10, 0x1400
	v_mov_b32_e32 v0, s10
	v_mov_b32_e32 v1, 1
	global_atomic_add v2, v0, v1, s[6:7] sc0
	buffer_inv sc1
	s_waitcnt vmcnt(0) lgkmcnt(0)
	v_readfirstlane_b32 s11, v2
	v_readfirstlane_b32 s15, v4
	v_readfirstlane_b32 s14, v5
	s_add_i32 s11, s11, 1
	s_mul_i32 s15, s15, s9
	s_cmp_lg_u32 s11, s15
	s_cbranch_scc1 .Lgb6_wait
	buffer_wbl2 sc1
	s_waitcnt vmcnt(0)
	s_mov_b64 exec, 0xffff
	v_mbcnt_lo_u32_b32 v3, -1, 0
	v_lshlrev_b32_e32 v3, 8, v3
	v_add_u32_e32 v3, 0x2480, v3
	v_mov_b32_e32 v1, 1
	global_atomic_add v3, v1, s[6:7]
	s_mov_b64 exec, 1

.Lgb6_done:
.LBB0_1238:
	s_or_b64 exec, exec, s[2:3]
	s_and_b64 s[2:3], s[78:79], exec
	v_readlane_b32 s2, v254, 24
	v_readlane_b32 s3, v254, 25
	v_mov_b32_e32 v8, v214
	s_cselect_b32 s86, 32, 36
	s_or_b64 s[2:3], s[78:79], s[2:3]
	s_waitcnt lgkmcnt(0)
	s_barrier
	v_readlane_b32 s30, v253, 0
	v_readfirstlane_b32 s8, v8
	s_mov_b64 s[6:7], -1
	s_mov_b64 s[4:5], 0
	s_and_b64 vcc, exec, s[2:3]
	s_cbranch_vccnz .LBB0_1240
	s_lshl_b32 s4, s30, 2
	s_and_b32 s4, s4, 28
	s_ashr_i32 s5, s30, 6
	s_add_i32 s4, s4, s5
	s_ashr_i32 s5, s4, 3
	s_mul_i32 s5, s5, 9
	s_and_b32 s4, s4, 7
	s_add_i32 s4, s4, s5
	s_add_i32 s16, s4, 1
	s_bfe_u32 s20, s30, 0x30003
	s_mov_b64 s[6:7], 0
	s_mov_b64 s[4:5], -1

.Lgb7_done:
.LBB0_1318:
	s_or_b64 exec, exec, s[2:3]
	v_mov_b32_e32 v0, v214
	v_readlane_b32 s3, v253, 0
	s_waitcnt lgkmcnt(0)
	s_barrier
	s_lshl_b32 s3, s3, 3
	v_readfirstlane_b32 s2, v0
	s_ashr_i32 s2, s2, 6
	s_add_i32 s2, s3, s2
	s_cmpk_gt_i32 s2, 0x23ff
	s_cbranch_scc1 .LBB0_1325
	v_readlane_b32 s4, v254, 57
	v_readlane_b32 s5, v254, 58
	s_and_b64 s[4:5], s[4:5], exec
	v_readlane_b32 s4, v253, 62
	v_lshlrev_b32_e32 v1, 2, v0
	v_readlane_b32 s5, v253, 63
	v_and_b32_e32 v2, 0xfc, v1
	s_cselect_b32 s5, s5, 0
	s_cselect_b32 s4, s4, 0
	v_lshlrev_b32_e32 v176, 2, v2
	v_lshl_add_u64 v[32:33], s[4:5], 0, v[176:177]
	v_readlane_b32 s4, v254, 53
	v_readlane_b32 s5, v254, 54
	v_readlane_b32 s8, v253, 7
	s_lshl_b64 s[6:7], s[50:51], 2
	v_lshl_add_u64 v[34:35], s[4:5], 0, v[176:177]
	s_mov_b64 s[4:5], 0x34000
	v_lshl_add_u64 v[36:37], v[34:35], 0, s[4:5]
	s_mov_b64 s[4:5], 0x35000
	v_readlane_b32 s22, v253, 21
	v_lshl_add_u64 v[40:41], v[34:35], 0, s[4:5]
	s_mov_b64 s[4:5], 0x35400
	v_readlane_b32 s23, v253, 22
	s_add_u32 s6, s22, s6
	v_lshl_add_u64 v[42:43], v[34:35], 0, s[4:5]
	s_mov_b64 s[4:5], 0x35800
	s_addc_u32 s7, s23, s7
	v_lshl_add_u64 v[44:45], v[34:35], 0, s[4:5]
	s_mov_b64 s[4:5], 0x35c00
	v_lshl_add_u64 v[38:39], s[6:7], 0, v[176:177]
	v_lshl_add_u64 v[46:47], v[34:35], 0, s[4:5]
	s_mov_b64 s[4:5], 0x1000
	v_lshl_add_u64 v[48:49], v[38:39], 0, s[4:5]
	s_mov_b64 s[4:5], 0x1400
	v_lshl_add_u64 v[50:51], v[38:39], 0, s[4:5]
	s_mov_b64 s[4:5], 0x1800
	v_lshl_add_u64 v[52:53], v[38:39], 0, s[4:5]
	s_mov_b64 s[4:5], 0x1c00
	s_ashr_i32 s3, s2, 31
	v_lshl_add_u64 v[54:55], v[38:39], 0, s[4:5]
	s_lshl_b64 s[4:5], s[2:3], 13
	v_and_b32_e32 v0, 63, v0
	v_lshl_or_b32 v56, v0, 4, s4
	v_mov_b32_e32 v57, s5
	s_lshl_b64 s[4:5], s[2:3], 12
	v_lshl_or_b32 v58, v0, 3, s4
	v_mov_b32_e32 v59, s5
	v_lshlrev_b32_e32 v176, 2, v2
	v_readlane_b32 s9, v253, 8
	v_readlane_b32 s10, v253, 9
	v_readlane_b32 s11, v253, 10
	v_readlane_b32 s12, v253, 11
	v_readlane_b32 s13, v253, 12
	v_readlane_b32 s14, v253, 13
	v_readlane_b32 s15, v253, 14
	v_readlane_b32 s16, v253, 15
	v_readlane_b32 s17, v253, 16
	v_readlane_b32 s18, v253, 17
	v_readlane_b32 s19, v253, 18
	v_readlane_b32 s20, v253, 19
	v_readlane_b32 s21, v253, 20
	s_branch .LBB0_1322

.Lnrm_p7_exit:
.LBB0_1325:
	s_waitcnt vmcnt(0)
	s_barrier
	s_mov_b64 s[2:3], exec
	v_readlane_b32 s4, v253, 42
	v_readlane_b32 s5, v253, 43
	s_and_b64 s[4:5], s[2:3], s[4:5]
	s_movk_i32 s92, 0x2c00
	s_mov_b64 exec, s[4:5]
	s_cbranch_execz .LBB0_1369
	v_readlane_b32 s6, v253, 39
	v_readlane_b32 s7, v253, 40
	v_readlane_b32 s8, v253, 41
	v_readlane_b32 s9, v255, 20
	v_mov_b32_e32 v0, 0x23fc0
	ds_read2_b32 v[4:5], v0 offset1:1
	s_add_i32 s9, s9, 1
	v_writelane_b32 v255, s9, 20
	s_lshl_b32 s10, s8, 8
	s_add_i32 s10, s10, 0x1400
	v_mov_b32_e32 v0, s10
	v_mov_b32_e32 v1, 1
	global_atomic_add v2, v0, v1, s[6:7] sc0
	buffer_inv sc1
	s_waitcnt vmcnt(0) lgkmcnt(0)
	v_readfirstlane_b32 s11, v2
	v_readfirstlane_b32 s15, v4
	v_readfirstlane_b32 s14, v5
	s_add_i32 s11, s11, 1
	s_mul_i32 s15, s15, s9
	s_cmp_lg_u32 s11, s15
	s_cbranch_scc1 .Lgb8_wait
	buffer_wbl2 sc1
	s_waitcnt vmcnt(0)
	s_mov_b64 exec, 0xffff
	v_mbcnt_lo_u32_b32 v3, -1, 0
	v_lshlrev_b32_e32 v3, 8, v3
	v_add_u32_e32 v3, 0x2480, v3
	v_mov_b32_e32 v1, 1
	global_atomic_add v3, v1, s[6:7]
	s_mov_b64 exec, 1

.Lgb8_done:
.LBB0_1369:
	s_or_b64 exec, exec, s[2:3]
	v_mov_b32_e32 v237, v214
	v_readlane_b32 s36, v253, 0
	s_mul_i32 s50, s86, 44
	s_waitcnt lgkmcnt(0)
	s_barrier
	s_cmp_lt_i32 s36, s50
	v_cndmask_b32_e64 v0, 0, 1, s[78:79]
	v_readfirstlane_b32 s28, v237
	s_cselect_b64 s[4:5], -1, 0
	s_cmp_ge_i32 s36, s50
	v_cmp_ne_u32_e64 s[78:79], 1, v0
	s_cbranch_scc1 .LBB0_1373
	s_ashr_i32 s3, s36, 31
	s_lshr_b32 s3, s3, 29
	s_add_i32 s3, s36, s3
	s_ashr_i32 s6, s3, 3
	s_and_b32 s3, s3, -8
	s_sub_i32 s3, s36, s3
	s_lshr_b32 s2, s50, 3
	s_lshr_b32 s7, s3, 31
	s_or_b32 s2, s2, s7
	s_mul_i32 s2, s3, s2
	s_add_i32 s2, s2, s6
	s_mul_hi_i32 s3, s2, 0x2e8ba2e9
	s_lshr_b32 s6, s3, 31
	s_ashr_i32 s3, s3, 6
	s_add_i32 s3, s3, s6
	s_lshl_b32 s6, s3, 3
	s_sub_i32 s7, s86, s6
	s_min_u32 s7, s7, 8
	s_mulk_i32 s3, 0x160
	s_sub_i32 s8, s2, s3
	v_cvt_f32_ubyte0_e32 v1, s7
	v_cvt_f32_i32_e32 v0, s8
	v_rcp_iflag_f32_e32 v2, v1
	s_ashr_i32 s2, s8, 30
	s_or_b32 s9, s2, 1
	v_mul_f32_e32 v2, v0, v2
	v_trunc_f32_e32 v2, v2
	v_fma_f32 v0, -v2, v1, v0
	v_cvt_i32_f32_e32 v2, v2
	v_cmp_ge_f32_e64 s[2:3], |v0|, v1
	s_and_b64 s[2:3], s[2:3], exec
	s_cselect_b32 s2, s9, 0
	v_readfirstlane_b32 s3, v2
	s_add_i32 s2, s3, s2
	s_mul_i32 s3, s2, s7
	s_sub_i32 s3, s8, s3
	s_sext_i32_i16 s3, s3
	s_and_b64 vcc, exec, s[78:79]
	s_add_i32 s30, s6, s3
	s_cbranch_vccnz .LBB0_1372
	s_ashr_i32 s6, s30, 3
	s_mul_i32 s6, s6, 9
	s_and_b32 s3, s3, 7
	s_add_i32 s3, s3, s6
	s_add_i32 s30, s3, 1

.LBB0_1702:
	s_waitcnt vmcnt(0)
	s_barrier
	s_mov_b64 s[56:57], exec
	v_readlane_b32 s4, v253, 42
	v_readlane_b32 s5, v253, 43
	s_and_b64 s[4:5], s[56:57], s[4:5]
	s_mov_b64 exec, s[4:5]
	s_cbranch_execz .LBB0_1746
	v_readlane_b32 s6, v253, 39
	v_readlane_b32 s7, v253, 40
	v_readlane_b32 s8, v253, 41
	v_readlane_b32 s9, v255, 20
	v_mov_b32_e32 v0, 0x23fc0
	ds_read2_b32 v[4:5], v0 offset1:1
	s_add_i32 s9, s9, 1
	v_writelane_b32 v255, s9, 20
	s_lshl_b32 s10, s8, 8
	s_add_i32 s10, s10, 0x1400
	v_mov_b32_e32 v0, s10
	v_mov_b32_e32 v1, 1
	global_atomic_add v2, v0, v1, s[6:7] sc0
	buffer_inv sc1
	s_waitcnt vmcnt(0) lgkmcnt(0)
	v_readfirstlane_b32 s11, v2
	v_readfirstlane_b32 s15, v4
	v_readfirstlane_b32 s14, v5
	s_add_i32 s11, s11, 1
	s_mul_i32 s15, s15, s9
	s_cmp_lg_u32 s11, s15
	s_cbranch_scc1 .Lgb9_wait
	s_mov_b64 exec, 0xffff
	v_mbcnt_lo_u32_b32 v3, -1, 0
	v_lshlrev_b32_e32 v3, 8, v3
	v_add_u32_e32 v3, 0x2480, v3
	v_mov_b32_e32 v1, 1
	global_atomic_add v3, v1, s[6:7]
	s_mov_b64 exec, 1

.Lgb9_done:
.LBB0_1746:
	s_or_b64 exec, exec, s[56:57]
	v_mov_b32_e32 v90, v214
	v_readlane_b32 s8, v253, 0
	s_waitcnt lgkmcnt(0)
	s_barrier
	s_lshl_b32 s5, s8, 2
	s_ashr_i32 s4, s8, 6
	s_and_b32 s5, s5, 28
	s_add_i32 s5, s5, s4
	s_mul_i32 s9, s4, 9
	s_ashr_i32 s4, s5, 3
	s_mul_i32 s4, s4, 9
	s_and_b32 s5, s5, 7
	s_add_i32 s33, s5, s4
	s_add_i32 s33, s33, 1
	s_ashr_i32 s36, s8, 31
	s_add_u32 s10, s54, 0xb000
	s_addc_u32 s11, s55, 0
	s_add_u32 s12, s54, 0x16000
	s_addc_u32 s13, s55, 0
	s_add_u32 s14, s54, 0x5800
	s_addc_u32 s15, s55, 0
	s_add_u32 s16, s54, 0x10800
	s_addc_u32 s17, s55, 0
	s_add_u32 s18, s54, 0x1b800
	s_movk_i32 s4, 0x57f
	s_addc_u32 s19, s55, 0
	v_cmp_lt_i32_e32 vcc, s4, v90
	s_add_u32 s20, s2, 0x5800
	s_addc_u32 s21, s3, 0
	s_mov_b32 s37, 0
	s_xor_b64 s[22:23], vcc, -1
	s_mov_b32 s26, s95

.Lfz_start:
	v_mov_b32_e32 v153, v150
	s_lshl_b32 s18, s95, 8
	s_add_i32 s18, s18, s35
	v_add_u32_e32 v152, s18, v128
	s_mul_i32 s18, s20, 0xc000
	s_add_u32 s18, s33, s18
	s_addc_u32 s19, s34, 0
	global_load_dwordx4 v[132:135], v153, s[18:19] offset:0
	global_load_dwordx4 v[136:139], v153, s[18:19] offset:64
	global_load_dwordx4 v[140:143], v153, s[18:19] offset:512
	global_load_dwordx4 v[244:247], v153, s[18:19] offset:576
	v_readlane_b32 s100, v253, 50
	v_readlane_b32 s101, v253, 51
	s_add_u32 s100, s100, 0
	s_addc_u32 s101, s101, 0
	v_add_u32_e32 v154, 0, v152
	v_lshl_add_u32 v154, v154, 13, v153
	global_load_dwordx4 v[160:163], v154, s[100:101] offset:0
	global_load_dwordx4 v[164:167], v154, s[100:101] offset:64
	global_load_dwordx4 v[168:171], v154, s[100:101] offset:512
	global_load_dwordx4 v[172:175], v154, s[100:101] offset:576
	v_add_u32_e32 v154, 16, v152
	v_lshl_add_u32 v154, v154, 13, v153
	global_load_dwordx4 v[180:183], v154, s[100:101] offset:0
	global_load_dwordx4 v[184:187], v154, s[100:101] offset:64
	global_load_dwordx4 v[188:191], v154, s[100:101] offset:512
	global_load_dwordx4 v[192:195], v154, s[100:101] offset:576
	v_add_u32_e32 v154, 32, v152
	v_lshl_add_u32 v154, v154, 13, v153
	global_load_dwordx4 v[196:199], v154, s[100:101] offset:0
	global_load_dwordx4 v[200:203], v154, s[100:101] offset:64
	global_load_dwordx4 v[204:207], v154, s[100:101] offset:512
	global_load_dwordx4 v[208:211], v154, s[100:101] offset:576
	v_add_u32_e32 v154, 48, v152
	v_lshl_add_u32 v154, v154, 13, v153
	global_load_dwordx4 v[220:223], v154, s[100:101] offset:0
	global_load_dwordx4 v[232:235], v154, s[100:101] offset:64
	global_load_dwordx4 v[236:239], v154, s[100:101] offset:512
	global_load_dwordx4 v[240:243], v154, s[100:101] offset:576
	s_waitcnt vmcnt(0)
	v_pk_fma_f32 v[124:125], v[124:125], v[132:133], v[160:161]
	v_pk_fma_f32 v[126:127], v[126:127], v[134:135], v[162:163]
	v_pk_fma_f32 v[120:121], v[120:121], v[136:137], v[164:165]
	v_pk_fma_f32 v[122:123], v[122:123], v[138:139], v[166:167]
	v_pk_fma_f32 v[104:105], v[104:105], v[140:141], v[168:169]
	v_pk_fma_f32 v[106:107], v[106:107], v[142:143], v[170:171]
	v_pk_fma_f32 v[96:97], v[96:97], v[244:245], v[172:173]
	v_pk_fma_f32 v[98:99], v[98:99], v[246:247], v[174:175]
	v_pk_fma_f32 v[116:117], v[116:117], v[132:133], v[180:181]
	v_pk_fma_f32 v[118:119], v[118:119], v[134:135], v[182:183]
	v_pk_fma_f32 v[112:113], v[112:113], v[136:137], v[184:185]
	v_pk_fma_f32 v[114:115], v[114:115], v[138:139], v[186:187]
	v_pk_fma_f32 v[88:89], v[88:89], v[140:141], v[188:189]
	v_pk_fma_f32 v[90:91], v[90:91], v[142:143], v[190:191]
	v_pk_fma_f32 v[84:85], v[84:85], v[244:245], v[192:193]
	v_pk_fma_f32 v[86:87], v[86:87], v[246:247], v[194:195]
	v_pk_fma_f32 v[108:109], v[108:109], v[132:133], v[196:197]
	v_pk_fma_f32 v[110:111], v[110:111], v[134:135], v[198:199]
	v_pk_fma_f32 v[100:101], v[100:101], v[136:137], v[200:201]
	v_pk_fma_f32 v[102:103], v[102:103], v[138:139], v[202:203]
	v_pk_fma_f32 v[80:81], v[80:81], v[140:141], v[204:205]
	v_pk_fma_f32 v[82:83], v[82:83], v[142:143], v[206:207]
	v_pk_fma_f32 v[76:77], v[76:77], v[244:245], v[208:209]
	v_pk_fma_f32 v[78:79], v[78:79], v[246:247], v[210:211]
	v_pk_fma_f32 v[92:93], v[92:93], v[132:133], v[220:221]
	v_pk_fma_f32 v[94:95], v[94:95], v[134:135], v[222:223]
	v_pk_fma_f32 v[72:73], v[72:73], v[136:137], v[232:233]
	v_pk_fma_f32 v[74:75], v[74:75], v[138:139], v[234:235]
	v_pk_fma_f32 v[68:69], v[68:69], v[140:141], v[236:237]
	v_pk_fma_f32 v[70:71], v[70:71], v[142:143], v[238:239]
	v_pk_fma_f32 v[64:65], v[64:65], v[244:245], v[240:241]
	v_pk_fma_f32 v[66:67], v[66:67], v[246:247], v[242:243]
	v_add_u32_e32 v154, 128, v152
	v_lshl_add_u32 v154, v154, 13, v153
	global_load_dwordx4 v[160:163], v154, s[100:101] offset:0
	global_load_dwordx4 v[164:167], v154, s[100:101] offset:64
	global_load_dwordx4 v[168:171], v154, s[100:101] offset:512
	global_load_dwordx4 v[172:175], v154, s[100:101] offset:576
	v_add_u32_e32 v154, 144, v152
	v_lshl_add_u32 v154, v154, 13, v153
	global_load_dwordx4 v[180:183], v154, s[100:101] offset:0
	global_load_dwordx4 v[184:187], v154, s[100:101] offset:64
	global_load_dwordx4 v[188:191], v154, s[100:101] offset:512
	global_load_dwordx4 v[192:195], v154, s[100:101] offset:576
	v_add_u32_e32 v154, 160, v152
	v_lshl_add_u32 v154, v154, 13, v153
	global_load_dwordx4 v[196:199], v154, s[100:101] offset:0
	global_load_dwordx4 v[200:203], v154, s[100:101] offset:64
	global_load_dwordx4 v[204:207], v154, s[100:101] offset:512
	global_load_dwordx4 v[208:211], v154, s[100:101] offset:576
	v_add_u32_e32 v154, 176, v152
	v_lshl_add_u32 v154, v154, 13, v153
	global_load_dwordx4 v[220:223], v154, s[100:101] offset:0
	global_load_dwordx4 v[232:235], v154, s[100:101] offset:64
	global_load_dwordx4 v[236:239], v154, s[100:101] offset:512
	global_load_dwordx4 v[240:243], v154, s[100:101] offset:576
	s_waitcnt vmcnt(0)
	v_pk_fma_f32 v[60:61], v[60:61], v[132:133], v[160:161]
	v_pk_fma_f32 v[62:63], v[62:63], v[134:135], v[162:163]
	v_pk_fma_f32 v[56:57], v[56:57], v[136:137], v[164:165]
	v_pk_fma_f32 v[58:59], v[58:59], v[138:139], v[166:167]
	v_pk_fma_f32 v[40:41], v[40:41], v[140:141], v[168:169]
	v_pk_fma_f32 v[42:43], v[42:43], v[142:143], v[170:171]
	v_pk_fma_f32 v[36:37], v[36:37], v[244:245], v[172:173]
	v_pk_fma_f32 v[38:39], v[38:39], v[246:247], v[174:175]
	v_pk_fma_f32 v[52:53], v[52:53], v[132:133], v[180:181]
	v_pk_fma_f32 v[54:55], v[54:55], v[134:135], v[182:183]
	v_pk_fma_f32 v[48:49], v[48:49], v[136:137], v[184:185]
	v_pk_fma_f32 v[50:51], v[50:51], v[138:139], v[186:187]
	v_pk_fma_f32 v[28:29], v[28:29], v[140:141], v[188:189]
	v_pk_fma_f32 v[30:31], v[30:31], v[142:143], v[190:191]
	v_pk_fma_f32 v[24:25], v[24:25], v[244:245], v[192:193]
	v_pk_fma_f32 v[26:27], v[26:27], v[246:247], v[194:195]
	v_pk_fma_f32 v[44:45], v[44:45], v[132:133], v[196:197]
	v_pk_fma_f32 v[46:47], v[46:47], v[134:135], v[198:199]
	v_pk_fma_f32 v[32:33], v[32:33], v[136:137], v[200:201]
	v_pk_fma_f32 v[34:35], v[34:35], v[138:139], v[202:203]
	v_pk_fma_f32 v[20:21], v[20:21], v[140:141], v[204:205]
	v_pk_fma_f32 v[22:23], v[22:23], v[142:143], v[206:207]
	v_pk_fma_f32 v[12:13], v[12:13], v[244:245], v[208:209]
	v_pk_fma_f32 v[14:15], v[14:15], v[246:247], v[210:211]
	v_pk_fma_f32 v[16:17], v[16:17], v[132:133], v[220:221]
	v_pk_fma_f32 v[18:19], v[18:19], v[134:135], v[222:223]
	v_pk_fma_f32 v[8:9], v[8:9], v[136:137], v[232:233]
	v_pk_fma_f32 v[10:11], v[10:11], v[138:139], v[234:235]
	v_pk_fma_f32 v[4:5], v[4:5], v[140:141], v[236:237]
	v_pk_fma_f32 v[6:7], v[6:7], v[142:143], v[238:239]
	v_pk_fma_f32 v[0:1], v[0:1], v[244:245], v[240:241]
	v_pk_fma_f32 v[2:3], v[2:3], v[246:247], v[242:243]
	v_readlane_b32 s18, v253, 1
	v_readlane_b32 s19, v253, 2
	s_add_u32 s18, s18, 0
	s_addc_u32 s19, s19, 0
	global_load_dwordx4 v[132:135], v153, s[18:19] offset:0
	global_load_dwordx4 v[136:139], v153, s[18:19] offset:64
	global_load_dwordx4 v[140:143], v153, s[18:19] offset:512
	global_load_dwordx4 v[244:247], v153, s[18:19] offset:576
	v_mul_f32_e32 v160, v124, v124
	v_fmac_f32_e32 v160, v125, v125
	v_fmac_f32_e32 v160, v126, v126
	v_fmac_f32_e32 v160, v127, v127
	v_fmac_f32_e32 v160, v120, v120
	v_fmac_f32_e32 v160, v121, v121
	v_fmac_f32_e32 v160, v122, v122
	v_fmac_f32_e32 v160, v123, v123
	v_fmac_f32_e32 v160, v104, v104
	v_fmac_f32_e32 v160, v105, v105
	v_fmac_f32_e32 v160, v106, v106
	v_fmac_f32_e32 v160, v107, v107
	v_fmac_f32_e32 v160, v96, v96
	v_fmac_f32_e32 v160, v97, v97
	v_fmac_f32_e32 v160, v98, v98
	v_fmac_f32_e32 v160, v99, v99
	v_mul_f32_e32 v161, v116, v116
	v_fmac_f32_e32 v161, v117, v117
	v_fmac_f32_e32 v161, v118, v118
	v_fmac_f32_e32 v161, v119, v119
	v_fmac_f32_e32 v161, v112, v112
	v_fmac_f32_e32 v161, v113, v113
	v_fmac_f32_e32 v161, v114, v114
	v_fmac_f32_e32 v161, v115, v115
	v_fmac_f32_e32 v161, v88, v88
	v_fmac_f32_e32 v161, v89, v89
	v_fmac_f32_e32 v161, v90, v90
	v_fmac_f32_e32 v161, v91, v91
	v_fmac_f32_e32 v161, v84, v84
	v_fmac_f32_e32 v161, v85, v85
	v_fmac_f32_e32 v161, v86, v86
	v_fmac_f32_e32 v161, v87, v87
	v_mul_f32_e32 v162, v108, v108
	v_fmac_f32_e32 v162, v109, v109
	v_fmac_f32_e32 v162, v110, v110
	v_fmac_f32_e32 v162, v111, v111
	v_fmac_f32_e32 v162, v100, v100
	v_fmac_f32_e32 v162, v101, v101
	v_fmac_f32_e32 v162, v102, v102
	v_fmac_f32_e32 v162, v103, v103
	v_fmac_f32_e32 v162, v80, v80
	v_fmac_f32_e32 v162, v81, v81
	v_fmac_f32_e32 v162, v82, v82
	v_fmac_f32_e32 v162, v83, v83
	v_fmac_f32_e32 v162, v76, v76
	v_fmac_f32_e32 v162, v77, v77
	v_fmac_f32_e32 v162, v78, v78
	v_fmac_f32_e32 v162, v79, v79
	v_mul_f32_e32 v163, v92, v92
	v_fmac_f32_e32 v163, v93, v93
	v_fmac_f32_e32 v163, v94, v94
	v_fmac_f32_e32 v163, v95, v95
	v_fmac_f32_e32 v163, v72, v72
	v_fmac_f32_e32 v163, v73, v73
	v_fmac_f32_e32 v163, v74, v74
	v_fmac_f32_e32 v163, v75, v75
	v_fmac_f32_e32 v163, v68, v68
	v_fmac_f32_e32 v163, v69, v69
	v_fmac_f32_e32 v163, v70, v70
	v_fmac_f32_e32 v163, v71, v71
	v_fmac_f32_e32 v163, v64, v64
	v_fmac_f32_e32 v163, v65, v65
	v_fmac_f32_e32 v163, v66, v66
	v_fmac_f32_e32 v163, v67, v67
	v_mul_f32_e32 v164, v60, v60
	v_fmac_f32_e32 v164, v61, v61
	v_fmac_f32_e32 v164, v62, v62
	v_fmac_f32_e32 v164, v63, v63
	v_fmac_f32_e32 v164, v56, v56
	v_fmac_f32_e32 v164, v57, v57
	v_fmac_f32_e32 v164, v58, v58
	v_fmac_f32_e32 v164, v59, v59
	v_fmac_f32_e32 v164, v40, v40
	v_fmac_f32_e32 v164, v41, v41
	v_fmac_f32_e32 v164, v42, v42
	v_fmac_f32_e32 v164, v43, v43
	v_fmac_f32_e32 v164, v36, v36
	v_fmac_f32_e32 v164, v37, v37
	v_fmac_f32_e32 v164, v38, v38
	v_fmac_f32_e32 v164, v39, v39
	v_mul_f32_e32 v165, v52, v52
	v_fmac_f32_e32 v165, v53, v53
	v_fmac_f32_e32 v165, v54, v54
	v_fmac_f32_e32 v165, v55, v55
	v_fmac_f32_e32 v165, v48, v48
	v_fmac_f32_e32 v165, v49, v49
	v_fmac_f32_e32 v165, v50, v50
	v_fmac_f32_e32 v165, v51, v51
	v_fmac_f32_e32 v165, v28, v28
	v_fmac_f32_e32 v165, v29, v29
	v_fmac_f32_e32 v165, v30, v30
	v_fmac_f32_e32 v165, v31, v31
	v_fmac_f32_e32 v165, v24, v24
	v_fmac_f32_e32 v165, v25, v25
	v_fmac_f32_e32 v165, v26, v26
	v_fmac_f32_e32 v165, v27, v27
	v_mul_f32_e32 v166, v44, v44
	v_fmac_f32_e32 v166, v45, v45
	v_fmac_f32_e32 v166, v46, v46
	v_fmac_f32_e32 v166, v47, v47
	v_fmac_f32_e32 v166, v32, v32
	v_fmac_f32_e32 v166, v33, v33
	v_fmac_f32_e32 v166, v34, v34
	v_fmac_f32_e32 v166, v35, v35
	v_fmac_f32_e32 v166, v20, v20
	v_fmac_f32_e32 v166, v21, v21
	v_fmac_f32_e32 v166, v22, v22
	v_fmac_f32_e32 v166, v23, v23
	v_fmac_f32_e32 v166, v12, v12
	v_fmac_f32_e32 v166, v13, v13
	v_fmac_f32_e32 v166, v14, v14
	v_fmac_f32_e32 v166, v15, v15
	v_mul_f32_e32 v167, v16, v16
	v_fmac_f32_e32 v167, v17, v17
	v_fmac_f32_e32 v167, v18, v18
	v_fmac_f32_e32 v167, v19, v19
	v_fmac_f32_e32 v167, v8, v8
	v_fmac_f32_e32 v167, v9, v9
	v_fmac_f32_e32 v167, v10, v10
	v_fmac_f32_e32 v167, v11, v11
	v_fmac_f32_e32 v167, v4, v4
	v_fmac_f32_e32 v167, v5, v5
	v_fmac_f32_e32 v167, v6, v6
	v_fmac_f32_e32 v167, v7, v7
	v_fmac_f32_e32 v167, v0, v0
	v_fmac_f32_e32 v167, v1, v1
	v_fmac_f32_e32 v167, v2, v2
	v_fmac_f32_e32 v167, v3, v3
	v_mov_b32_e32 v168, v160
	v_mov_b32_e32 v169, v161
	v_mov_b32_e32 v170, v162
	v_mov_b32_e32 v171, v163
	v_mov_b32_e32 v172, v164
	v_mov_b32_e32 v173, v165
	v_mov_b32_e32 v174, v166
	v_mov_b32_e32 v175, v167
	s_nop 1
	v_permlane32_swap_b32_e32 v160, v168
	v_permlane32_swap_b32_e32 v161, v169
	v_permlane32_swap_b32_e32 v162, v170
	v_permlane32_swap_b32_e32 v163, v171
	v_permlane32_swap_b32_e32 v164, v172
	v_permlane32_swap_b32_e32 v165, v173
	v_permlane32_swap_b32_e32 v166, v174
	v_permlane32_swap_b32_e32 v167, v175
	s_nop 1
	v_add_f32_e32 v160, v160, v168
	v_add_f32_e32 v161, v161, v169
	v_add_f32_e32 v162, v162, v170
	v_add_f32_e32 v163, v163, v171
	v_add_f32_e32 v164, v164, v172
	v_add_f32_e32 v165, v165, v173
	v_add_f32_e32 v166, v166, v174
	v_add_f32_e32 v167, v167, v175
	v_mov_b32_e32 v168, v160
	v_mov_b32_e32 v169, v161
	v_mov_b32_e32 v170, v162
	v_mov_b32_e32 v171, v163
	v_mov_b32_e32 v172, v164
	v_mov_b32_e32 v173, v165
	v_mov_b32_e32 v174, v166
	v_mov_b32_e32 v175, v167
	s_nop 1
	v_permlane16_swap_b32_e32 v160, v168
	v_permlane16_swap_b32_e32 v161, v169
	v_permlane16_swap_b32_e32 v162, v170
	v_permlane16_swap_b32_e32 v163, v171
	v_permlane16_swap_b32_e32 v164, v172
	v_permlane16_swap_b32_e32 v165, v173
	v_permlane16_swap_b32_e32 v166, v174
	v_permlane16_swap_b32_e32 v167, v175
	s_nop 1
	v_add_f32_e32 v160, v160, v168
	v_add_f32_e32 v161, v161, v169
	v_add_f32_e32 v162, v162, v170
	v_add_f32_e32 v163, v163, v171
	v_add_f32_e32 v164, v164, v172
	v_add_f32_e32 v165, v165, v173
	v_add_f32_e32 v166, v166, v174
	v_add_f32_e32 v167, v167, v175
	s_lshr_b32 s18, s35, 6
	s_lshl_b32 s18, s18, 2
	s_lshr_b32 s19, s36, 5
	s_add_i32 s18, s18, s19
	s_lshl_b32 s18, s18, 9
	s_add_i32 s18, s18, 0x20000
	v_lshl_add_u32 v154, v128, 2, s18
	ds_write_b32 v154, v160 offset:0
	ds_write_b32 v154, v161 offset:64
	ds_write_b32 v154, v162 offset:128
	ds_write_b32 v154, v163 offset:192
	ds_write_b32 v154, v164 offset:256
	ds_write_b32 v154, v165 offset:320
	ds_write_b32 v154, v166 offset:384
	ds_write_b32 v154, v167 offset:448
	s_waitcnt lgkmcnt(0)
	s_barrier
	s_lshr_b32 s18, s35, 6
	s_lshl_b32 s18, s18, 11
	s_add_i32 s18, s18, 0x20000
	v_lshl_add_u32 v154, v128, 2, s18
	ds_read_b32 v180, v154 offset:0
	ds_read_b32 v181, v154 offset:512
	ds_read_b32 v182, v154 offset:1024
	ds_read_b32 v183, v154 offset:1536
	ds_read_b32 v184, v154 offset:64
	ds_read_b32 v185, v154 offset:576
	ds_read_b32 v186, v154 offset:1088
	ds_read_b32 v187, v154 offset:1600
	ds_read_b32 v188, v154 offset:128
	ds_read_b32 v189, v154 offset:640
	ds_read_b32 v190, v154 offset:1152
	ds_read_b32 v191, v154 offset:1664
	ds_read_b32 v192, v154 offset:192
	ds_read_b32 v193, v154 offset:704
	ds_read_b32 v194, v154 offset:1216
	ds_read_b32 v195, v154 offset:1728
	ds_read_b32 v196, v154 offset:256
	ds_read_b32 v197, v154 offset:768
	ds_read_b32 v198, v154 offset:1280
	ds_read_b32 v199, v154 offset:1792
	ds_read_b32 v200, v154 offset:320
	ds_read_b32 v201, v154 offset:832
	ds_read_b32 v202, v154 offset:1344
	ds_read_b32 v203, v154 offset:1856
	ds_read_b32 v204, v154 offset:384
	ds_read_b32 v205, v154 offset:896
	ds_read_b32 v206, v154 offset:1408
	ds_read_b32 v207, v154 offset:1920
	ds_read_b32 v208, v154 offset:448
	ds_read_b32 v209, v154 offset:960
	ds_read_b32 v210, v154 offset:1472
	ds_read_b32 v211, v154 offset:1984
	s_waitcnt lgkmcnt(0)
	v_add_f32_e32 v160, v180, v181
	v_add_f32_e32 v160, v160, v182
	v_add_f32_e32 v160, v160, v183
	v_add_f32_e32 v161, v184, v185
	v_add_f32_e32 v161, v161, v186
	v_add_f32_e32 v161, v161, v187
	v_add_f32_e32 v162, v188, v189
	v_add_f32_e32 v162, v162, v190
	v_add_f32_e32 v162, v162, v191
	v_add_f32_e32 v163, v192, v193
	v_add_f32_e32 v163, v163, v194
	v_add_f32_e32 v163, v163, v195
	v_add_f32_e32 v164, v196, v197
	v_add_f32_e32 v164, v164, v198
	v_add_f32_e32 v164, v164, v199
	v_add_f32_e32 v165, v200, v201
	v_add_f32_e32 v165, v165, v202
	v_add_f32_e32 v165, v165, v203
	v_add_f32_e32 v166, v204, v205
	v_add_f32_e32 v166, v166, v206
	v_add_f32_e32 v166, v166, v207
	v_add_f32_e32 v167, v208, v209
	v_add_f32_e32 v167, v167, v210
	v_add_f32_e32 v167, v167, v211
	v_readlane_b32 s100, v254, 48
	v_readlane_b32 s101, v254, 49
	s_add_u32 s100, s100, 0x90000
	s_addc_u32 s101, s101, 0
	s_cmp_lg_u32 s36, 0
	s_cbranch_scc1 .Lfz_nopub
	s_mul_i32 s18, s92, 0x2400
	v_add_u32_e32 v154, s18, v152
	v_lshlrev_b32_e32 v154, 2, v154
	global_store_dword v154, v160, s[100:101] offset:0 sc1
	global_store_dword v154, v161, s[100:101] offset:64 sc1
	global_store_dword v154, v162, s[100:101] offset:128 sc1
	global_store_dword v154, v163, s[100:101] offset:192 sc1
	global_store_dword v154, v164, s[100:101] offset:512 sc1
	global_store_dword v154, v165, s[100:101] offset:576 sc1
	global_store_dword v154, v166, s[100:101] offset:640 sc1
	global_store_dword v154, v167, s[100:101] offset:704 sc1

.Lfz_synced:
	s_mov_b64 exec, s[20:21]
	s_barrier
	v_mul_u32_u24_e32 v154, 0x4800, v129
	v_add_u32_e32 v154, v154, v152
	v_lshlrev_b32_e32 v154, 2, v154
	v_add_u32_e32 v155, 0x9000, v154
	global_load_dword v180, v154, s[100:101] offset:0 sc1
	global_load_dword v181, v155, s[100:101] offset:0 sc1
	global_load_dword v182, v154, s[100:101] offset:64 sc1
	global_load_dword v183, v155, s[100:101] offset:64 sc1
	global_load_dword v184, v154, s[100:101] offset:128 sc1
	global_load_dword v185, v155, s[100:101] offset:128 sc1
	global_load_dword v186, v154, s[100:101] offset:192 sc1
	global_load_dword v187, v155, s[100:101] offset:192 sc1
	global_load_dword v188, v154, s[100:101] offset:512 sc1
	global_load_dword v189, v155, s[100:101] offset:512 sc1
	global_load_dword v190, v154, s[100:101] offset:576 sc1
	global_load_dword v191, v155, s[100:101] offset:576 sc1
	global_load_dword v192, v154, s[100:101] offset:640 sc1
	global_load_dword v193, v155, s[100:101] offset:640 sc1
	global_load_dword v194, v154, s[100:101] offset:704 sc1
	global_load_dword v195, v155, s[100:101] offset:704 sc1
	s_waitcnt vmcnt(0)
	v_add_f32_e32 v160, v180, v181
	v_add_f32_e32 v161, v182, v183
	v_add_f32_e32 v162, v184, v185
	v_add_f32_e32 v163, v186, v187
	v_add_f32_e32 v164, v188, v189
	v_add_f32_e32 v165, v190, v191
	v_add_f32_e32 v166, v192, v193
	v_add_f32_e32 v167, v194, v195
	v_mov_b32_e32 v168, v160
	v_mov_b32_e32 v169, v161
	v_mov_b32_e32 v170, v162
	v_mov_b32_e32 v171, v163
	v_mov_b32_e32 v172, v164
	v_mov_b32_e32 v173, v165
	v_mov_b32_e32 v174, v166
	v_mov_b32_e32 v175, v167
	s_nop 1
	v_permlane32_swap_b32_e32 v160, v168
	v_permlane32_swap_b32_e32 v161, v169
	v_permlane32_swap_b32_e32 v162, v170
	v_permlane32_swap_b32_e32 v163, v171
	v_permlane32_swap_b32_e32 v164, v172
	v_permlane32_swap_b32_e32 v165, v173
	v_permlane32_swap_b32_e32 v166, v174
	v_permlane32_swap_b32_e32 v167, v175
	s_nop 1
	v_add_f32_e32 v160, v160, v168
	v_add_f32_e32 v161, v161, v169
	v_add_f32_e32 v162, v162, v170
	v_add_f32_e32 v163, v163, v171
	v_add_f32_e32 v164, v164, v172
	v_add_f32_e32 v165, v165, v173
	v_add_f32_e32 v166, v166, v174
	v_add_f32_e32 v167, v167, v175
	v_mov_b32_e32 v168, v160
	v_mov_b32_e32 v169, v161
	v_mov_b32_e32 v170, v162
	v_mov_b32_e32 v171, v163
	v_mov_b32_e32 v172, v164
	v_mov_b32_e32 v173, v165
	v_mov_b32_e32 v174, v166
	v_mov_b32_e32 v175, v167
	s_nop 1
	v_permlane16_swap_b32_e32 v160, v168
	v_permlane16_swap_b32_e32 v161, v169
	v_permlane16_swap_b32_e32 v162, v170
	v_permlane16_swap_b32_e32 v163, v171
	v_permlane16_swap_b32_e32 v164, v172
	v_permlane16_swap_b32_e32 v165, v173
	v_permlane16_swap_b32_e32 v166, v174
	v_permlane16_swap_b32_e32 v167, v175
	s_nop 1
	v_add_f32_e32 v160, v160, v168
	v_add_f32_e32 v161, v161, v169
	v_add_f32_e32 v162, v162, v170
	v_add_f32_e32 v163, v163, v171
	v_add_f32_e32 v164, v164, v172
	v_add_f32_e32 v165, v165, v173
	v_add_f32_e32 v166, v166, v174
	v_add_f32_e32 v167, v167, v175
	v_mov_b32_e32 v178, 0x358637bd
	v_mov_b32_e32 v179, 0x260
	v_fmamk_f32 v160, v160, 0x3a000000, v178
	v_mul_f32_e32 v169, 0x4f800000, v160
	v_cmp_gt_f32_e32 vcc, 0xf800000, v160
	s_nop 1
	v_cndmask_b32_e32 v168, v160, v169, vcc
	v_sqrt_f32_e32 v169, v168
	s_nop 0
	v_add_u32_e32 v170, -1, v169
	v_fma_f32 v171, -v170, v169, v168
	v_cmp_ge_f32_e64 s[18:19], 0, v171
	v_add_u32_e32 v171, 1, v169
	s_nop 0
	v_cndmask_b32_e64 v170, v169, v170, s[18:19]
	v_fma_f32 v169, -v171, v169, v168
	v_cmp_lt_f32_e64 s[18:19], 0, v169
	s_nop 1
	v_cndmask_b32_e64 v169, v170, v171, s[18:19]
	v_mul_f32_e32 v170, 0x37800000, v169
	v_cndmask_b32_e32 v169, v169, v170, vcc
	v_cmp_class_f32_e32 vcc, v168, v179
	s_nop 1
	v_cndmask_b32_e32 v168, v169, v168, vcc
	v_div_scale_f32 v169, s[18:19], v168, v168, 1.0
	v_rcp_f32_e32 v170, v169
	s_nop 1
	v_fma_f32 v171, -v169, v170, 1.0
	v_fmac_f32_e32 v170, v171, v170
	v_div_scale_f32 v171, vcc, 1.0, v168, 1.0
	v_mul_f32_e32 v172, v171, v170
	v_fma_f32 v173, -v169, v172, v171
	v_fmac_f32_e32 v172, v173, v170
	v_fma_f32 v169, -v169, v172, v171
	s_nop 0
	v_div_fmas_f32 v169, v169, v170, v172
	v_div_fixup_f32 v180, v169, v168, 1.0
	v_fmamk_f32 v161, v161, 0x3a000000, v178
	v_mul_f32_e32 v169, 0x4f800000, v161
	v_cmp_gt_f32_e32 vcc, 0xf800000, v161
	s_nop 1
	v_cndmask_b32_e32 v168, v161, v169, vcc
	v_sqrt_f32_e32 v169, v168
	s_nop 0
	v_add_u32_e32 v170, -1, v169
	v_fma_f32 v171, -v170, v169, v168
	v_cmp_ge_f32_e64 s[18:19], 0, v171
	v_add_u32_e32 v171, 1, v169
	s_nop 0
	v_cndmask_b32_e64 v170, v169, v170, s[18:19]
	v_fma_f32 v169, -v171, v169, v168
	v_cmp_lt_f32_e64 s[18:19], 0, v169
	s_nop 1
	v_cndmask_b32_e64 v169, v170, v171, s[18:19]
	v_mul_f32_e32 v170, 0x37800000, v169
	v_cndmask_b32_e32 v169, v169, v170, vcc
	v_cmp_class_f32_e32 vcc, v168, v179
	s_nop 1
	v_cndmask_b32_e32 v168, v169, v168, vcc
	v_div_scale_f32 v169, s[18:19], v168, v168, 1.0
	v_rcp_f32_e32 v170, v169
	s_nop 1
	v_fma_f32 v171, -v169, v170, 1.0
	v_fmac_f32_e32 v170, v171, v170
	v_div_scale_f32 v171, vcc, 1.0, v168, 1.0
	v_mul_f32_e32 v172, v171, v170
	v_fma_f32 v173, -v169, v172, v171
	v_fmac_f32_e32 v172, v173, v170
	v_fma_f32 v169, -v169, v172, v171
	s_nop 0
	v_div_fmas_f32 v169, v169, v170, v172
	v_div_fixup_f32 v182, v169, v168, 1.0
	v_fmamk_f32 v162, v162, 0x3a000000, v178
	v_mul_f32_e32 v169, 0x4f800000, v162
	v_cmp_gt_f32_e32 vcc, 0xf800000, v162
	s_nop 1
	v_cndmask_b32_e32 v168, v162, v169, vcc
	v_sqrt_f32_e32 v169, v168
	s_nop 0
	v_add_u32_e32 v170, -1, v169
	v_fma_f32 v171, -v170, v169, v168
	v_cmp_ge_f32_e64 s[18:19], 0, v171
	v_add_u32_e32 v171, 1, v169
	s_nop 0
	v_cndmask_b32_e64 v170, v169, v170, s[18:19]
	v_fma_f32 v169, -v171, v169, v168
	v_cmp_lt_f32_e64 s[18:19], 0, v169
	s_nop 1
	v_cndmask_b32_e64 v169, v170, v171, s[18:19]
	v_mul_f32_e32 v170, 0x37800000, v169
	v_cndmask_b32_e32 v169, v169, v170, vcc
	v_cmp_class_f32_e32 vcc, v168, v179
	s_nop 1
	v_cndmask_b32_e32 v168, v169, v168, vcc
	v_div_scale_f32 v169, s[18:19], v168, v168, 1.0
	v_rcp_f32_e32 v170, v169
	s_nop 1
	v_fma_f32 v171, -v169, v170, 1.0
	v_fmac_f32_e32 v170, v171, v170
	v_div_scale_f32 v171, vcc, 1.0, v168, 1.0
	v_mul_f32_e32 v172, v171, v170
	v_fma_f32 v173, -v169, v172, v171
	v_fmac_f32_e32 v172, v173, v170
	v_fma_f32 v169, -v169, v172, v171
	s_nop 0
	v_div_fmas_f32 v169, v169, v170, v172
	v_div_fixup_f32 v184, v169, v168, 1.0
	v_fmamk_f32 v163, v163, 0x3a000000, v178
	v_mul_f32_e32 v169, 0x4f800000, v163
	v_cmp_gt_f32_e32 vcc, 0xf800000, v163
	s_nop 1
	v_cndmask_b32_e32 v168, v163, v169, vcc
	v_sqrt_f32_e32 v169, v168
	s_nop 0
	v_add_u32_e32 v170, -1, v169
	v_fma_f32 v171, -v170, v169, v168
	v_cmp_ge_f32_e64 s[18:19], 0, v171
	v_add_u32_e32 v171, 1, v169
	s_nop 0
	v_cndmask_b32_e64 v170, v169, v170, s[18:19]
	v_fma_f32 v169, -v171, v169, v168
	v_cmp_lt_f32_e64 s[18:19], 0, v169
	s_nop 1
	v_cndmask_b32_e64 v169, v170, v171, s[18:19]
	v_mul_f32_e32 v170, 0x37800000, v169
	v_cndmask_b32_e32 v169, v169, v170, vcc
	v_cmp_class_f32_e32 vcc, v168, v179
	s_nop 1
	v_cndmask_b32_e32 v168, v169, v168, vcc
	v_div_scale_f32 v169, s[18:19], v168, v168, 1.0
	v_rcp_f32_e32 v170, v169
	s_nop 1
	v_fma_f32 v171, -v169, v170, 1.0
	v_fmac_f32_e32 v170, v171, v170
	v_div_scale_f32 v171, vcc, 1.0, v168, 1.0
	v_mul_f32_e32 v172, v171, v170
	v_fma_f32 v173, -v169, v172, v171
	v_fmac_f32_e32 v172, v173, v170
	v_fma_f32 v169, -v169, v172, v171
	s_nop 0
	v_div_fmas_f32 v169, v169, v170, v172
	v_div_fixup_f32 v186, v169, v168, 1.0
	v_fmamk_f32 v164, v164, 0x3a000000, v178
	v_mul_f32_e32 v169, 0x4f800000, v164
	v_cmp_gt_f32_e32 vcc, 0xf800000, v164
	s_nop 1
	v_cndmask_b32_e32 v168, v164, v169, vcc
	v_sqrt_f32_e32 v169, v168
	s_nop 0
	v_add_u32_e32 v170, -1, v169
	v_fma_f32 v171, -v170, v169, v168
	v_cmp_ge_f32_e64 s[18:19], 0, v171
	v_add_u32_e32 v171, 1, v169
	s_nop 0
	v_cndmask_b32_e64 v170, v169, v170, s[18:19]
	v_fma_f32 v169, -v171, v169, v168
	v_cmp_lt_f32_e64 s[18:19], 0, v169
	s_nop 1
	v_cndmask_b32_e64 v169, v170, v171, s[18:19]
	v_mul_f32_e32 v170, 0x37800000, v169
	v_cndmask_b32_e32 v169, v169, v170, vcc
	v_cmp_class_f32_e32 vcc, v168, v179
	s_nop 1
	v_cndmask_b32_e32 v168, v169, v168, vcc
	v_div_scale_f32 v169, s[18:19], v168, v168, 1.0
	v_rcp_f32_e32 v170, v169
	s_nop 1
	v_fma_f32 v171, -v169, v170, 1.0
	v_fmac_f32_e32 v170, v171, v170
	v_div_scale_f32 v171, vcc, 1.0, v168, 1.0
	v_mul_f32_e32 v172, v171, v170
	v_fma_f32 v173, -v169, v172, v171
	v_fmac_f32_e32 v172, v173, v170
	v_fma_f32 v169, -v169, v172, v171
	s_nop 0
	v_div_fmas_f32 v169, v169, v170, v172
	v_div_fixup_f32 v188, v169, v168, 1.0
	v_fmamk_f32 v165, v165, 0x3a000000, v178
	v_mul_f32_e32 v169, 0x4f800000, v165
	v_cmp_gt_f32_e32 vcc, 0xf800000, v165
	s_nop 1
	v_cndmask_b32_e32 v168, v165, v169, vcc
	v_sqrt_f32_e32 v169, v168
	s_nop 0
	v_add_u32_e32 v170, -1, v169
	v_fma_f32 v171, -v170, v169, v168
	v_cmp_ge_f32_e64 s[18:19], 0, v171
	v_add_u32_e32 v171, 1, v169
	s_nop 0
	v_cndmask_b32_e64 v170, v169, v170, s[18:19]
	v_fma_f32 v169, -v171, v169, v168
	v_cmp_lt_f32_e64 s[18:19], 0, v169
	s_nop 1
	v_cndmask_b32_e64 v169, v170, v171, s[18:19]
	v_mul_f32_e32 v170, 0x37800000, v169
	v_cndmask_b32_e32 v169, v169, v170, vcc
	v_cmp_class_f32_e32 vcc, v168, v179
	s_nop 1
	v_cndmask_b32_e32 v168, v169, v168, vcc
	v_div_scale_f32 v169, s[18:19], v168, v168, 1.0
	v_rcp_f32_e32 v170, v169
	s_nop 1
	v_fma_f32 v171, -v169, v170, 1.0
	v_fmac_f32_e32 v170, v171, v170
	v_div_scale_f32 v171, vcc, 1.0, v168, 1.0
	v_mul_f32_e32 v172, v171, v170
	v_fma_f32 v173, -v169, v172, v171
	v_fmac_f32_e32 v172, v173, v170
	v_fma_f32 v169, -v169, v172, v171
	s_nop 0
	v_div_fmas_f32 v169, v169, v170, v172
	v_div_fixup_f32 v190, v169, v168, 1.0
	v_fmamk_f32 v166, v166, 0x3a000000, v178
	v_mul_f32_e32 v169, 0x4f800000, v166
	v_cmp_gt_f32_e32 vcc, 0xf800000, v166
	s_nop 1
	v_cndmask_b32_e32 v168, v166, v169, vcc
	v_sqrt_f32_e32 v169, v168
	s_nop 0
	v_add_u32_e32 v170, -1, v169
	v_fma_f32 v171, -v170, v169, v168
	v_cmp_ge_f32_e64 s[18:19], 0, v171
	v_add_u32_e32 v171, 1, v169
	s_nop 0
	v_cndmask_b32_e64 v170, v169, v170, s[18:19]
	v_fma_f32 v169, -v171, v169, v168
	v_cmp_lt_f32_e64 s[18:19], 0, v169
	s_nop 1
	v_cndmask_b32_e64 v169, v170, v171, s[18:19]
	v_mul_f32_e32 v170, 0x37800000, v169
	v_cndmask_b32_e32 v169, v169, v170, vcc
	v_cmp_class_f32_e32 vcc, v168, v179
	s_nop 1
	v_cndmask_b32_e32 v168, v169, v168, vcc
	v_div_scale_f32 v169, s[18:19], v168, v168, 1.0
	v_rcp_f32_e32 v170, v169
	s_nop 1
	v_fma_f32 v171, -v169, v170, 1.0
	v_fmac_f32_e32 v170, v171, v170
	v_div_scale_f32 v171, vcc, 1.0, v168, 1.0
	v_mul_f32_e32 v172, v171, v170
	v_fma_f32 v173, -v169, v172, v171
	v_fmac_f32_e32 v172, v173, v170
	v_fma_f32 v169, -v169, v172, v171
	s_nop 0
	v_div_fmas_f32 v169, v169, v170, v172
	v_div_fixup_f32 v192, v169, v168, 1.0
	v_fmamk_f32 v167, v167, 0x3a000000, v178
	v_mul_f32_e32 v169, 0x4f800000, v167
	v_cmp_gt_f32_e32 vcc, 0xf800000, v167
	s_nop 1
	v_cndmask_b32_e32 v168, v167, v169, vcc
	v_sqrt_f32_e32 v169, v168
	s_nop 0
	v_add_u32_e32 v170, -1, v169
	v_fma_f32 v171, -v170, v169, v168
	v_cmp_ge_f32_e64 s[18:19], 0, v171
	v_add_u32_e32 v171, 1, v169
	s_nop 0
	v_cndmask_b32_e64 v170, v169, v170, s[18:19]
	v_fma_f32 v169, -v171, v169, v168
	v_cmp_lt_f32_e64 s[18:19], 0, v169
	s_nop 1
	v_cndmask_b32_e64 v169, v170, v171, s[18:19]
	v_mul_f32_e32 v170, 0x37800000, v169
	v_cndmask_b32_e32 v169, v169, v170, vcc
	v_cmp_class_f32_e32 vcc, v168, v179
	s_nop 1
	v_cndmask_b32_e32 v168, v169, v168, vcc
	v_div_scale_f32 v169, s[18:19], v168, v168, 1.0
	v_rcp_f32_e32 v170, v169
	s_nop 1
	v_fma_f32 v171, -v169, v170, 1.0
	v_fmac_f32_e32 v170, v171, v170
	v_div_scale_f32 v171, vcc, 1.0, v168, 1.0
	v_mul_f32_e32 v172, v171, v170
	v_fma_f32 v173, -v169, v172, v171
	v_fmac_f32_e32 v172, v173, v170
	v_fma_f32 v169, -v169, v172, v171
	s_nop 0
	v_div_fmas_f32 v169, v169, v170, v172
	v_div_fixup_f32 v194, v169, v168, 1.0
	v_readlane_b32 s100, v253, 3
	v_readlane_b32 s101, v253, 4
	s_add_u32 s100, s100, 0
	s_addc_u32 s101, s101, 0
	s_mul_hi_i32 s18, s95, 0x38e38e39
	s_lshr_b32 s19, s18, 31
	s_ashr_i32 s18, s18, 1
	s_add_i32 s18, s18, s19
	s_add_i32 s18, s18, 1
	s_lshl_b32 s18, s18, 8
	v_subrev_u32_e32 v152, s18, v152
	s_waitcnt vmcnt(0)
	v_add_u32_e32 v154, 0, v152
	v_lshl_add_u32 v154, v154, 13, v153
	v_pk_mul_f32 v[124:125], v[124:125], v[180:181] op_sel_hi:[1,0]
	v_pk_mul_f32 v[126:127], v[126:127], v[180:181] op_sel_hi:[1,0]
	v_pk_mul_f32 v[124:125], v[124:125], v[132:133]
	v_pk_mul_f32 v[126:127], v[126:127], v[134:135]
	v_pk_mul_f32 v[120:121], v[120:121], v[180:181] op_sel_hi:[1,0]
	v_pk_mul_f32 v[122:123], v[122:123], v[180:181] op_sel_hi:[1,0]
	v_pk_mul_f32 v[120:121], v[120:121], v[136:137]
	v_pk_mul_f32 v[122:123], v[122:123], v[138:139]
	v_pk_mul_f32 v[104:105], v[104:105], v[180:181] op_sel_hi:[1,0]
	v_pk_mul_f32 v[106:107], v[106:107], v[180:181] op_sel_hi:[1,0]
	v_pk_mul_f32 v[104:105], v[104:105], v[140:141]
	v_pk_mul_f32 v[106:107], v[106:107], v[142:143]
	v_pk_mul_f32 v[96:97], v[96:97], v[180:181] op_sel_hi:[1,0]
	v_pk_mul_f32 v[98:99], v[98:99], v[180:181] op_sel_hi:[1,0]
	v_pk_mul_f32 v[96:97], v[96:97], v[244:245]
	v_pk_mul_f32 v[98:99], v[98:99], v[246:247]
	global_store_dwordx4 v154, v[124:127], s[100:101] offset:0
	global_store_dwordx4 v154, v[120:123], s[100:101] offset:64
	global_store_dwordx4 v154, v[104:107], s[100:101] offset:512
	global_store_dwordx4 v154, v[96:99], s[100:101] offset:576
	v_add_u32_e32 v154, 16, v152
	v_lshl_add_u32 v154, v154, 13, v153
	v_pk_mul_f32 v[116:117], v[116:117], v[182:183] op_sel_hi:[1,0]
	v_pk_mul_f32 v[118:119], v[118:119], v[182:183] op_sel_hi:[1,0]
	v_pk_mul_f32 v[116:117], v[116:117], v[132:133]
	v_pk_mul_f32 v[118:119], v[118:119], v[134:135]
	v_pk_mul_f32 v[112:113], v[112:113], v[182:183] op_sel_hi:[1,0]
	v_pk_mul_f32 v[114:115], v[114:115], v[182:183] op_sel_hi:[1,0]
	v_pk_mul_f32 v[112:113], v[112:113], v[136:137]
	v_pk_mul_f32 v[114:115], v[114:115], v[138:139]
	v_pk_mul_f32 v[88:89], v[88:89], v[182:183] op_sel_hi:[1,0]
	v_pk_mul_f32 v[90:91], v[90:91], v[182:183] op_sel_hi:[1,0]
	v_pk_mul_f32 v[88:89], v[88:89], v[140:141]
	v_pk_mul_f32 v[90:91], v[90:91], v[142:143]
	v_pk_mul_f32 v[84:85], v[84:85], v[182:183] op_sel_hi:[1,0]
	v_pk_mul_f32 v[86:87], v[86:87], v[182:183] op_sel_hi:[1,0]
	v_pk_mul_f32 v[84:85], v[84:85], v[244:245]
	v_pk_mul_f32 v[86:87], v[86:87], v[246:247]
	global_store_dwordx4 v154, v[116:119], s[100:101] offset:0
	global_store_dwordx4 v154, v[112:115], s[100:101] offset:64
	global_store_dwordx4 v154, v[88:91], s[100:101] offset:512
	global_store_dwordx4 v154, v[84:87], s[100:101] offset:576
	v_add_u32_e32 v154, 32, v152
	v_lshl_add_u32 v154, v154, 13, v153
	v_pk_mul_f32 v[108:109], v[108:109], v[184:185] op_sel_hi:[1,0]
	v_pk_mul_f32 v[110:111], v[110:111], v[184:185] op_sel_hi:[1,0]
	v_pk_mul_f32 v[108:109], v[108:109], v[132:133]
	v_pk_mul_f32 v[110:111], v[110:111], v[134:135]
	v_pk_mul_f32 v[100:101], v[100:101], v[184:185] op_sel_hi:[1,0]
	v_pk_mul_f32 v[102:103], v[102:103], v[184:185] op_sel_hi:[1,0]
	v_pk_mul_f32 v[100:101], v[100:101], v[136:137]
	v_pk_mul_f32 v[102:103], v[102:103], v[138:139]
	v_pk_mul_f32 v[80:81], v[80:81], v[184:185] op_sel_hi:[1,0]
	v_pk_mul_f32 v[82:83], v[82:83], v[184:185] op_sel_hi:[1,0]
	v_pk_mul_f32 v[80:81], v[80:81], v[140:141]
	v_pk_mul_f32 v[82:83], v[82:83], v[142:143]
	v_pk_mul_f32 v[76:77], v[76:77], v[184:185] op_sel_hi:[1,0]
	v_pk_mul_f32 v[78:79], v[78:79], v[184:185] op_sel_hi:[1,0]
	v_pk_mul_f32 v[76:77], v[76:77], v[244:245]
	v_pk_mul_f32 v[78:79], v[78:79], v[246:247]
	global_store_dwordx4 v154, v[108:111], s[100:101] offset:0
	global_store_dwordx4 v154, v[100:103], s[100:101] offset:64
	global_store_dwordx4 v154, v[80:83], s[100:101] offset:512
	global_store_dwordx4 v154, v[76:79], s[100:101] offset:576
	v_add_u32_e32 v154, 48, v152
	v_lshl_add_u32 v154, v154, 13, v153
	v_pk_mul_f32 v[92:93], v[92:93], v[186:187] op_sel_hi:[1,0]
	v_pk_mul_f32 v[94:95], v[94:95], v[186:187] op_sel_hi:[1,0]
	v_pk_mul_f32 v[92:93], v[92:93], v[132:133]
	v_pk_mul_f32 v[94:95], v[94:95], v[134:135]
	v_pk_mul_f32 v[72:73], v[72:73], v[186:187] op_sel_hi:[1,0]
	v_pk_mul_f32 v[74:75], v[74:75], v[186:187] op_sel_hi:[1,0]
	v_pk_mul_f32 v[72:73], v[72:73], v[136:137]
	v_pk_mul_f32 v[74:75], v[74:75], v[138:139]
	v_pk_mul_f32 v[68:69], v[68:69], v[186:187] op_sel_hi:[1,0]
	v_pk_mul_f32 v[70:71], v[70:71], v[186:187] op_sel_hi:[1,0]
	v_pk_mul_f32 v[68:69], v[68:69], v[140:141]
	v_pk_mul_f32 v[70:71], v[70:71], v[142:143]
	v_pk_mul_f32 v[64:65], v[64:65], v[186:187] op_sel_hi:[1,0]
	v_pk_mul_f32 v[66:67], v[66:67], v[186:187] op_sel_hi:[1,0]
	v_pk_mul_f32 v[64:65], v[64:65], v[244:245]
	v_pk_mul_f32 v[66:67], v[66:67], v[246:247]
	global_store_dwordx4 v154, v[92:95], s[100:101] offset:0
	global_store_dwordx4 v154, v[72:75], s[100:101] offset:64
	global_store_dwordx4 v154, v[68:71], s[100:101] offset:512
	global_store_dwordx4 v154, v[64:67], s[100:101] offset:576
	v_add_u32_e32 v154, 128, v152
	v_lshl_add_u32 v154, v154, 13, v153
	v_pk_mul_f32 v[60:61], v[60:61], v[188:189] op_sel_hi:[1,0]
	v_pk_mul_f32 v[62:63], v[62:63], v[188:189] op_sel_hi:[1,0]
	v_pk_mul_f32 v[60:61], v[60:61], v[132:133]
	v_pk_mul_f32 v[62:63], v[62:63], v[134:135]
	v_pk_mul_f32 v[56:57], v[56:57], v[188:189] op_sel_hi:[1,0]
	v_pk_mul_f32 v[58:59], v[58:59], v[188:189] op_sel_hi:[1,0]
	v_pk_mul_f32 v[56:57], v[56:57], v[136:137]
	v_pk_mul_f32 v[58:59], v[58:59], v[138:139]
	v_pk_mul_f32 v[40:41], v[40:41], v[188:189] op_sel_hi:[1,0]
	v_pk_mul_f32 v[42:43], v[42:43], v[188:189] op_sel_hi:[1,0]
	v_pk_mul_f32 v[40:41], v[40:41], v[140:141]
	v_pk_mul_f32 v[42:43], v[42:43], v[142:143]
	v_pk_mul_f32 v[36:37], v[36:37], v[188:189] op_sel_hi:[1,0]
	v_pk_mul_f32 v[38:39], v[38:39], v[188:189] op_sel_hi:[1,0]
	v_pk_mul_f32 v[36:37], v[36:37], v[244:245]
	v_pk_mul_f32 v[38:39], v[38:39], v[246:247]
	global_store_dwordx4 v154, v[60:63], s[100:101] offset:0
	global_store_dwordx4 v154, v[56:59], s[100:101] offset:64
	global_store_dwordx4 v154, v[40:43], s[100:101] offset:512
	global_store_dwordx4 v154, v[36:39], s[100:101] offset:576
	v_add_u32_e32 v154, 144, v152
	v_lshl_add_u32 v154, v154, 13, v153
	v_pk_mul_f32 v[52:53], v[52:53], v[190:191] op_sel_hi:[1,0]
	v_pk_mul_f32 v[54:55], v[54:55], v[190:191] op_sel_hi:[1,0]
	v_pk_mul_f32 v[52:53], v[52:53], v[132:133]
	v_pk_mul_f32 v[54:55], v[54:55], v[134:135]
	v_pk_mul_f32 v[48:49], v[48:49], v[190:191] op_sel_hi:[1,0]
	v_pk_mul_f32 v[50:51], v[50:51], v[190:191] op_sel_hi:[1,0]
	v_pk_mul_f32 v[48:49], v[48:49], v[136:137]
	v_pk_mul_f32 v[50:51], v[50:51], v[138:139]
	v_pk_mul_f32 v[28:29], v[28:29], v[190:191] op_sel_hi:[1,0]
	v_pk_mul_f32 v[30:31], v[30:31], v[190:191] op_sel_hi:[1,0]
	v_pk_mul_f32 v[28:29], v[28:29], v[140:141]
	v_pk_mul_f32 v[30:31], v[30:31], v[142:143]
	v_pk_mul_f32 v[24:25], v[24:25], v[190:191] op_sel_hi:[1,0]
	v_pk_mul_f32 v[26:27], v[26:27], v[190:191] op_sel_hi:[1,0]
	v_pk_mul_f32 v[24:25], v[24:25], v[244:245]
	v_pk_mul_f32 v[26:27], v[26:27], v[246:247]
	global_store_dwordx4 v154, v[52:55], s[100:101] offset:0
	global_store_dwordx4 v154, v[48:51], s[100:101] offset:64
	global_store_dwordx4 v154, v[28:31], s[100:101] offset:512
	global_store_dwordx4 v154, v[24:27], s[100:101] offset:576
	v_add_u32_e32 v154, 160, v152
	v_lshl_add_u32 v154, v154, 13, v153
	v_pk_mul_f32 v[44:45], v[44:45], v[192:193] op_sel_hi:[1,0]
	v_pk_mul_f32 v[46:47], v[46:47], v[192:193] op_sel_hi:[1,0]
	v_pk_mul_f32 v[44:45], v[44:45], v[132:133]
	v_pk_mul_f32 v[46:47], v[46:47], v[134:135]
	v_pk_mul_f32 v[32:33], v[32:33], v[192:193] op_sel_hi:[1,0]
	v_pk_mul_f32 v[34:35], v[34:35], v[192:193] op_sel_hi:[1,0]
	v_pk_mul_f32 v[32:33], v[32:33], v[136:137]
	v_pk_mul_f32 v[34:35], v[34:35], v[138:139]
	v_pk_mul_f32 v[20:21], v[20:21], v[192:193] op_sel_hi:[1,0]
	v_pk_mul_f32 v[22:23], v[22:23], v[192:193] op_sel_hi:[1,0]
	v_pk_mul_f32 v[20:21], v[20:21], v[140:141]
	v_pk_mul_f32 v[22:23], v[22:23], v[142:143]
	v_pk_mul_f32 v[12:13], v[12:13], v[192:193] op_sel_hi:[1,0]
	v_pk_mul_f32 v[14:15], v[14:15], v[192:193] op_sel_hi:[1,0]
	v_pk_mul_f32 v[12:13], v[12:13], v[244:245]
	v_pk_mul_f32 v[14:15], v[14:15], v[246:247]
	global_store_dwordx4 v154, v[44:47], s[100:101] offset:0
	global_store_dwordx4 v154, v[32:35], s[100:101] offset:64
	global_store_dwordx4 v154, v[20:23], s[100:101] offset:512
	global_store_dwordx4 v154, v[12:15], s[100:101] offset:576
	v_add_u32_e32 v154, 176, v152
	v_lshl_add_u32 v154, v154, 13, v153
	v_pk_mul_f32 v[16:17], v[16:17], v[194:195] op_sel_hi:[1,0]
	v_pk_mul_f32 v[18:19], v[18:19], v[194:195] op_sel_hi:[1,0]
	v_pk_mul_f32 v[16:17], v[16:17], v[132:133]
	v_pk_mul_f32 v[18:19], v[18:19], v[134:135]
	v_pk_mul_f32 v[8:9], v[8:9], v[194:195] op_sel_hi:[1,0]
	v_pk_mul_f32 v[10:11], v[10:11], v[194:195] op_sel_hi:[1,0]
	v_pk_mul_f32 v[8:9], v[8:9], v[136:137]
	v_pk_mul_f32 v[10:11], v[10:11], v[138:139]
	v_pk_mul_f32 v[4:5], v[4:5], v[194:195] op_sel_hi:[1,0]
	v_pk_mul_f32 v[6:7], v[6:7], v[194:195] op_sel_hi:[1,0]
	v_pk_mul_f32 v[4:5], v[4:5], v[140:141]
	v_pk_mul_f32 v[6:7], v[6:7], v[142:143]
	v_pk_mul_f32 v[0:1], v[0:1], v[194:195] op_sel_hi:[1,0]
	v_pk_mul_f32 v[2:3], v[2:3], v[194:195] op_sel_hi:[1,0]
	v_pk_mul_f32 v[0:1], v[0:1], v[244:245]
	v_pk_mul_f32 v[2:3], v[2:3], v[246:247]
	global_store_dwordx4 v154, v[16:19], s[100:101] offset:0
	global_store_dwordx4 v154, v[8:11], s[100:101] offset:64
	global_store_dwordx4 v154, v[4:7], s[100:101] offset:512
	global_store_dwordx4 v154, v[0:3], s[100:101] offset:576
	s_branch .LBB0_1807

.LBB0_1813:
	s_cmp_eq_u64 s[78:79], 0
	s_cbranch_scc1 .LBB0_1859
	s_waitcnt vmcnt(0)
	s_waitcnt vmcnt(0)
	s_barrier
	s_mov_b64 s[2:3], exec
	v_readlane_b32 s4, v253, 42
	v_readlane_b32 s5, v253, 43
	s_and_b64 s[4:5], s[2:3], s[4:5]
	s_movk_i32 s72, 0x1000
	s_mov_b32 s92, 0xf800000
	v_readlane_b32 s95, v254, 59
	s_mov_b64 exec, s[4:5]
	s_cbranch_execz .Lgb10_skip
	v_readlane_b32 s6, v253, 39
	v_readlane_b32 s7, v253, 40
	v_readlane_b32 s8, v253, 41
	v_readlane_b32 s9, v255, 20
	v_mov_b32_e32 v0, 0x23fc0
	ds_read2_b32 v[4:5], v0 offset1:1
	s_add_i32 s9, s9, 1
	v_writelane_b32 v255, s9, 20
	s_lshl_b32 s10, s8, 8
	s_add_i32 s10, s10, 0x1400
	v_mov_b32_e32 v0, s10
	v_mov_b32_e32 v1, 1
	global_atomic_add v2, v0, v1, s[6:7] sc0
	buffer_inv sc1
	s_waitcnt vmcnt(0) lgkmcnt(0)
	v_readfirstlane_b32 s11, v2
	v_readfirstlane_b32 s15, v4
	v_readfirstlane_b32 s14, v5
	s_add_i32 s11, s11, 1
	s_mul_i32 s15, s15, s9
	s_cmp_lg_u32 s11, s15
	s_cbranch_scc1 .Lgb10_wait
	s_mov_b64 exec, 0xffff
	v_mbcnt_lo_u32_b32 v3, -1, 0
	v_lshlrev_b32_e32 v3, 8, v3
	v_add_u32_e32 v3, 0x2480, v3
	v_mov_b32_e32 v1, 1
	global_atomic_add v3, v1, s[6:7]
	s_mov_b64 exec, 1

.Lgb10_done:
.Lgb10_skip:
	s_getpc_b64 s[98:99]

.LBB0_1856:
	s_branch .LBB0_1859
.LBB0_1859:
	s_endpgm
